# merge GEMM epilogues (EpiMerge 0/1/2) rewritten as a 4-deep software pipeline of gate/prev loads; on top of MLA pipelining, batched scan, v_rcp sigmoid/silu
# speedup vs baseline: 1.0469x; 1.0075x over previous
; __device__ __forceinline__ u32x4 pack8(const float* v) { u32x4 w; w.x = pk2(v[0], v[1]); w.y = pk2(v[2], v[3]); w.z = pk2(v[4], v[5]); w.w = pk2(v[6], v[7]); return w; }
; __device__ __forceinline__ void unpack8(u32x4 w, float* v) { v[0] = bflo(w.x); v[1] = bfhi(w.x); v[2] = bflo(w.y); v[3] = bfhi(w.y); v[4] = bflo(w.z); v[5] = bfhi(w.z); v[6] = bflo(w.w); v[7] = bfhi(w.w); }
; #define EPI_LOOP_END asm volatile("" ::: "memory"); } }
;     __device__ __forceinline__ void operator()(const f32x4 (&acc)[2][2][4][2], const pg8::Unit& u, int wr, int wc, int fr, int fq) const {
;         EPI_LOOP_BEGIN
;             float g[8]; unpack8(*(const u32x4*)((const bf16_t*)(ws + O_GATES) + (size_t)t * 3072 + PASS * 1024 + c0), g);
;             bf16_t* mp = (bf16_t*)(ws + O_HM) + (size_t)t * 1024 + c0;
;             if (PASS > 0) { float pv[8]; unpack8(*(const u32x4*)mp, pv);
; #pragma unroll
;                 for (int e = 0; e < 8; ++e) v[e] = pv[e] + g[e] * v[e];
;             } else {
; #pragma unroll
;                 for (int e = 0; e < 8; ++e) v[e] *= g[e];
;             }
;             *(u32x4*)mp = pack8(v);
;         EPI_LOOP_END
;     }
.LBB0_275:
	v_mov_b32_e32 v150, v41
	v_mov_b32_e32 v148, v37
	s_lshl_b32 s0, s66, 8
	s_or_b32 s0, s0, s58
	v_lshl_add_u32 v148, v148, 3, s0
	s_lshl_b32 s0, s67, 8
	s_add_i32 s0, s0, s57
	v_ashrrev_i32_e32 v149, 31, v148
	v_add_u32_e32 v154, s0, v150
	v_mul_u32_u24_e32 v149, 0x1800, v154
	v_lshl_add_u32 v149, v148, 1, v149
	v_lshlrev_b32_e32 v155, 11, v154
	v_lshl_add_u32 v155, v148, 1, v155
	global_load_dwordx4 v[150:153], v149, s[34:35]
	v_add_u32_e32 v208, 0x18000, v149
	global_load_dwordx4 v[174:177], v208, s[34:35]
	v_add_u32_e32 v208, 0x30000, v149
	global_load_dwordx4 v[178:181], v208, s[34:35]
	v_add_u32_e32 v208, 0x48000, v149
	global_load_dwordx4 v[182:185], v208, s[34:35]
	s_waitcnt vmcnt(3)
	v_lshlrev_b32_e32 v158, 16, v150
	v_and_b32_e32 v159, 0xffff0000, v150
	v_lshlrev_b32_e32 v160, 16, v151
	v_and_b32_e32 v161, 0xffff0000, v151
	v_lshlrev_b32_e32 v162, 16, v152
	v_and_b32_e32 v163, 0xffff0000, v152
	v_lshlrev_b32_e32 v164, 16, v153
	v_and_b32_e32 v165, 0xffff0000, v153
	v_pk_mul_f32 v[136:137], v[136:137], v[158:159]
	v_pk_mul_f32 v[138:139], v[138:139], v[160:161]
	v_pk_mul_f32 v[132:133], v[132:133], v[162:163]
	v_pk_mul_f32 v[134:135], v[134:135], v[164:165]
	v_cvt_pk_bf16_f32 v158, v136, v137
	v_cvt_pk_bf16_f32 v159, v138, v139
	v_cvt_pk_bf16_f32 v160, v132, v133
	v_cvt_pk_bf16_f32 v161, v134, v135
	global_store_dwordx4 v155, v[158:161], s[20:21]
	v_add_u32_e32 v208, 0xc0000, v149
	global_load_dwordx4 v[150:153], v208, s[34:35]
	s_waitcnt vmcnt(4)
	v_lshlrev_b32_e32 v158, 16, v174
	v_and_b32_e32 v159, 0xffff0000, v174
	v_lshlrev_b32_e32 v160, 16, v175
	v_and_b32_e32 v161, 0xffff0000, v175
	v_lshlrev_b32_e32 v162, 16, v176
	v_and_b32_e32 v163, 0xffff0000, v176
	v_lshlrev_b32_e32 v164, 16, v177
	v_and_b32_e32 v165, 0xffff0000, v177
	v_pk_mul_f32 v[128:129], v[128:129], v[158:159]
	v_pk_mul_f32 v[130:131], v[130:131], v[160:161]
	v_pk_mul_f32 v[124:125], v[124:125], v[162:163]
	v_pk_mul_f32 v[126:127], v[126:127], v[164:165]
	v_cvt_pk_bf16_f32 v158, v128, v129
	v_cvt_pk_bf16_f32 v159, v130, v131
	v_cvt_pk_bf16_f32 v160, v124, v125
	v_cvt_pk_bf16_f32 v161, v126, v127
	v_add_u32_e32 v209, 0x8000, v155
	global_store_dwordx4 v209, v[158:161], s[20:21]
	v_add_u32_e32 v208, 0xd8000, v149
	global_load_dwordx4 v[174:177], v208, s[34:35]
	s_waitcnt vmcnt(5)
	v_lshlrev_b32_e32 v158, 16, v178
	v_and_b32_e32 v159, 0xffff0000, v178
	v_lshlrev_b32_e32 v160, 16, v179
	v_and_b32_e32 v161, 0xffff0000, v179
	v_lshlrev_b32_e32 v162, 16, v180
	v_and_b32_e32 v163, 0xffff0000, v180
	v_lshlrev_b32_e32 v164, 16, v181
	v_and_b32_e32 v165, 0xffff0000, v181
	v_pk_mul_f32 v[120:121], v[120:121], v[158:159]
	v_pk_mul_f32 v[122:123], v[122:123], v[160:161]
	v_pk_mul_f32 v[116:117], v[116:117], v[162:163]
	v_pk_mul_f32 v[118:119], v[118:119], v[164:165]
	v_cvt_pk_bf16_f32 v158, v120, v121
	v_cvt_pk_bf16_f32 v159, v122, v123
	v_cvt_pk_bf16_f32 v160, v116, v117
	v_cvt_pk_bf16_f32 v161, v118, v119
	v_add_u32_e32 v209, 0x10000, v155
	global_store_dwordx4 v209, v[158:161], s[20:21]
	v_add_u32_e32 v208, 0xf0000, v149
	global_load_dwordx4 v[178:181], v208, s[34:35]
	s_waitcnt vmcnt(6)
	v_lshlrev_b32_e32 v158, 16, v182
	v_and_b32_e32 v159, 0xffff0000, v182
	v_lshlrev_b32_e32 v160, 16, v183
	v_and_b32_e32 v161, 0xffff0000, v183
	v_lshlrev_b32_e32 v162, 16, v184
	v_and_b32_e32 v163, 0xffff0000, v184
	v_lshlrev_b32_e32 v164, 16, v185
	v_and_b32_e32 v165, 0xffff0000, v185
	v_pk_mul_f32 v[112:113], v[112:113], v[158:159]
	v_pk_mul_f32 v[114:115], v[114:115], v[160:161]
	v_pk_mul_f32 v[108:109], v[108:109], v[162:163]
	v_pk_mul_f32 v[110:111], v[110:111], v[164:165]
	v_cvt_pk_bf16_f32 v158, v112, v113
	v_cvt_pk_bf16_f32 v159, v114, v115
	v_cvt_pk_bf16_f32 v160, v108, v109
	v_cvt_pk_bf16_f32 v161, v110, v111
	v_add_u32_e32 v209, 0x18000, v155
	global_store_dwordx4 v209, v[158:161], s[20:21]
	v_add_u32_e32 v208, 0x108000, v149
	global_load_dwordx4 v[182:185], v208, s[34:35]
	s_waitcnt vmcnt(6)
	v_lshlrev_b32_e32 v158, 16, v150
	v_and_b32_e32 v159, 0xffff0000, v150
	v_lshlrev_b32_e32 v160, 16, v151
	v_and_b32_e32 v161, 0xffff0000, v151
	v_lshlrev_b32_e32 v162, 16, v152
	v_and_b32_e32 v163, 0xffff0000, v152
	v_lshlrev_b32_e32 v164, 16, v153
	v_and_b32_e32 v165, 0xffff0000, v153
	v_pk_mul_f32 v[104:105], v[104:105], v[158:159]
	v_pk_mul_f32 v[106:107], v[106:107], v[160:161]
	v_pk_mul_f32 v[100:101], v[100:101], v[162:163]
	v_pk_mul_f32 v[102:103], v[102:103], v[164:165]
	v_cvt_pk_bf16_f32 v158, v104, v105
	v_cvt_pk_bf16_f32 v159, v106, v107
	v_cvt_pk_bf16_f32 v160, v100, v101
	v_cvt_pk_bf16_f32 v161, v102, v103
	v_add_u32_e32 v209, 0x40000, v155
	global_store_dwordx4 v209, v[158:161], s[20:21]
	v_add_u32_e32 v208, 0x100, v149
	global_load_dwordx4 v[150:153], v208, s[34:35]
	s_waitcnt vmcnt(6)
	v_lshlrev_b32_e32 v158, 16, v174
	v_and_b32_e32 v159, 0xffff0000, v174
	v_lshlrev_b32_e32 v160, 16, v175
	v_and_b32_e32 v161, 0xffff0000, v175
	v_lshlrev_b32_e32 v162, 16, v176
	v_and_b32_e32 v163, 0xffff0000, v176
	v_lshlrev_b32_e32 v164, 16, v177
	v_and_b32_e32 v165, 0xffff0000, v177
	v_pk_mul_f32 v[96:97], v[96:97], v[158:159]
	v_pk_mul_f32 v[98:99], v[98:99], v[160:161]
	v_pk_mul_f32 v[92:93], v[92:93], v[162:163]
	v_pk_mul_f32 v[94:95], v[94:95], v[164:165]
	v_cvt_pk_bf16_f32 v158, v96, v97
	v_cvt_pk_bf16_f32 v159, v98, v99
	v_cvt_pk_bf16_f32 v160, v92, v93
	v_cvt_pk_bf16_f32 v161, v94, v95
	v_add_u32_e32 v209, 0x48000, v155
	global_store_dwordx4 v209, v[158:161], s[20:21]
	v_add_u32_e32 v208, 0x18100, v149
	global_load_dwordx4 v[174:177], v208, s[34:35]
	s_waitcnt vmcnt(6)
; __device__ __forceinline__ u32x4 pack8(const float* v) { u32x4 w; w.x = pk2(v[0], v[1]); w.y = pk2(v[2], v[3]); w.z = pk2(v[4], v[5]); w.w = pk2(v[6], v[7]); return w; }
; __device__ __forceinline__ void unpack8(u32x4 w, float* v) { v[0] = bflo(w.x); v[1] = bfhi(w.x); v[2] = bflo(w.y); v[3] = bfhi(w.y); v[4] = bflo(w.z); v[5] = bfhi(w.z); v[6] = bflo(w.w); v[7] = bfhi(w.w); }
; #define EPI_LOOP_END asm volatile("" ::: "memory"); } }
;     __device__ __forceinline__ void operator()(const f32x4 (&acc)[2][2][4][2], const pg8::Unit& u, int wr, int wc, int fr, int fq) const {
;         EPI_LOOP_BEGIN
;             float g[8]; unpack8(*(const u32x4*)((const bf16_t*)(ws + O_GATES) + (size_t)t * 3072 + PASS * 1024 + c0), g);
;             bf16_t* mp = (bf16_t*)(ws + O_HM) + (size_t)t * 1024 + c0;
;             if (PASS > 0) { float pv[8]; unpack8(*(const u32x4*)mp, pv);
; #pragma unroll
;                 for (int e = 0; e < 8; ++e) v[e] = pv[e] + g[e] * v[e];
;             } else {
; #pragma unroll
;                 for (int e = 0; e < 8; ++e) v[e] *= g[e];
;             }
;             *(u32x4*)mp = pack8(v);
;         EPI_LOOP_END
;     }
	v_lshlrev_b32_e32 v158, 16, v178
	v_and_b32_e32 v159, 0xffff0000, v178
	v_lshlrev_b32_e32 v160, 16, v179
	v_and_b32_e32 v161, 0xffff0000, v179
	v_lshlrev_b32_e32 v162, 16, v180
	v_and_b32_e32 v163, 0xffff0000, v180
	v_lshlrev_b32_e32 v164, 16, v181
	v_and_b32_e32 v165, 0xffff0000, v181
	v_pk_mul_f32 v[88:89], v[88:89], v[158:159]
	v_pk_mul_f32 v[90:91], v[90:91], v[160:161]
	v_pk_mul_f32 v[84:85], v[84:85], v[162:163]
	v_pk_mul_f32 v[86:87], v[86:87], v[164:165]
	v_cvt_pk_bf16_f32 v158, v88, v89
	v_cvt_pk_bf16_f32 v159, v90, v91
	v_cvt_pk_bf16_f32 v160, v84, v85
	v_cvt_pk_bf16_f32 v161, v86, v87
	v_add_u32_e32 v209, 0x50000, v155
	global_store_dwordx4 v209, v[158:161], s[20:21]
	v_add_u32_e32 v208, 0x30100, v149
	global_load_dwordx4 v[178:181], v208, s[34:35]
	s_waitcnt vmcnt(6)
	v_lshlrev_b32_e32 v158, 16, v182
	v_and_b32_e32 v159, 0xffff0000, v182
	v_lshlrev_b32_e32 v160, 16, v183
	v_and_b32_e32 v161, 0xffff0000, v183
	v_lshlrev_b32_e32 v162, 16, v184
	v_and_b32_e32 v163, 0xffff0000, v184
	v_lshlrev_b32_e32 v164, 16, v185
	v_and_b32_e32 v165, 0xffff0000, v185
	v_pk_mul_f32 v[80:81], v[80:81], v[158:159]
	v_pk_mul_f32 v[82:83], v[82:83], v[160:161]
	v_pk_mul_f32 v[76:77], v[76:77], v[162:163]
	v_pk_mul_f32 v[78:79], v[78:79], v[164:165]
	v_cvt_pk_bf16_f32 v158, v80, v81
	v_cvt_pk_bf16_f32 v159, v82, v83
	v_cvt_pk_bf16_f32 v160, v76, v77
	v_cvt_pk_bf16_f32 v161, v78, v79
	v_add_u32_e32 v209, 0x58000, v155
	global_store_dwordx4 v209, v[158:161], s[20:21]
	v_add_u32_e32 v208, 0x48100, v149
	global_load_dwordx4 v[182:185], v208, s[34:35]
	s_waitcnt vmcnt(6)
	v_lshlrev_b32_e32 v158, 16, v150
	v_and_b32_e32 v159, 0xffff0000, v150
	v_lshlrev_b32_e32 v160, 16, v151
	v_and_b32_e32 v161, 0xffff0000, v151
	v_lshlrev_b32_e32 v162, 16, v152
	v_and_b32_e32 v163, 0xffff0000, v152
	v_lshlrev_b32_e32 v164, 16, v153
	v_and_b32_e32 v165, 0xffff0000, v153
	v_pk_mul_f32 v[72:73], v[72:73], v[158:159]
	v_pk_mul_f32 v[74:75], v[74:75], v[160:161]
	v_pk_mul_f32 v[68:69], v[68:69], v[162:163]
	v_pk_mul_f32 v[70:71], v[70:71], v[164:165]
	v_cvt_pk_bf16_f32 v158, v72, v73
	v_cvt_pk_bf16_f32 v159, v74, v75
	v_cvt_pk_bf16_f32 v160, v68, v69
	v_cvt_pk_bf16_f32 v161, v70, v71
	v_add_u32_e32 v209, 0x100, v155
	global_store_dwordx4 v209, v[158:161], s[20:21]
	v_add_u32_e32 v208, 0xc0100, v149
	global_load_dwordx4 v[150:153], v208, s[34:35]
	s_waitcnt vmcnt(6)
	v_lshlrev_b32_e32 v158, 16, v174
	v_and_b32_e32 v159, 0xffff0000, v174
	v_lshlrev_b32_e32 v160, 16, v175
	v_and_b32_e32 v161, 0xffff0000, v175
	v_lshlrev_b32_e32 v162, 16, v176
	v_and_b32_e32 v163, 0xffff0000, v176
	v_lshlrev_b32_e32 v164, 16, v177
	v_and_b32_e32 v165, 0xffff0000, v177
	v_pk_mul_f32 v[64:65], v[64:65], v[158:159]
	v_pk_mul_f32 v[66:67], v[66:67], v[160:161]
	v_pk_mul_f32 v[60:61], v[60:61], v[162:163]
	v_pk_mul_f32 v[62:63], v[62:63], v[164:165]
	v_cvt_pk_bf16_f32 v158, v64, v65
	v_cvt_pk_bf16_f32 v159, v66, v67
	v_cvt_pk_bf16_f32 v160, v60, v61
	v_cvt_pk_bf16_f32 v161, v62, v63
	v_add_u32_e32 v209, 0x8100, v155
	global_store_dwordx4 v209, v[158:161], s[20:21]
	v_add_u32_e32 v208, 0xd8100, v149
	global_load_dwordx4 v[174:177], v208, s[34:35]
	s_waitcnt vmcnt(6)
	v_lshlrev_b32_e32 v158, 16, v178
	v_and_b32_e32 v159, 0xffff0000, v178
	v_lshlrev_b32_e32 v160, 16, v179
	v_and_b32_e32 v161, 0xffff0000, v179
	v_lshlrev_b32_e32 v162, 16, v180
	v_and_b32_e32 v163, 0xffff0000, v180
	v_lshlrev_b32_e32 v164, 16, v181
	v_and_b32_e32 v165, 0xffff0000, v181
	v_pk_mul_f32 v[56:57], v[56:57], v[158:159]
	v_pk_mul_f32 v[58:59], v[58:59], v[160:161]
	v_pk_mul_f32 v[52:53], v[52:53], v[162:163]
	v_pk_mul_f32 v[54:55], v[54:55], v[164:165]
	v_cvt_pk_bf16_f32 v158, v56, v57
	v_cvt_pk_bf16_f32 v159, v58, v59
	v_cvt_pk_bf16_f32 v160, v52, v53
	v_cvt_pk_bf16_f32 v161, v54, v55
	v_add_u32_e32 v209, 0x10100, v155
	global_store_dwordx4 v209, v[158:161], s[20:21]
	v_add_u32_e32 v208, 0xf0100, v149
	global_load_dwordx4 v[178:181], v208, s[34:35]
	s_waitcnt vmcnt(6)
; __device__ __forceinline__ u32x4 pack8(const float* v) { u32x4 w; w.x = pk2(v[0], v[1]); w.y = pk2(v[2], v[3]); w.z = pk2(v[4], v[5]); w.w = pk2(v[6], v[7]); return w; }
; __device__ __forceinline__ void unpack8(u32x4 w, float* v) { v[0] = bflo(w.x); v[1] = bfhi(w.x); v[2] = bflo(w.y); v[3] = bfhi(w.y); v[4] = bflo(w.z); v[5] = bfhi(w.z); v[6] = bflo(w.w); v[7] = bfhi(w.w); }
; #define EPI_LOOP_END asm volatile("" ::: "memory"); } }
;     __device__ __forceinline__ void operator()(const f32x4 (&acc)[2][2][4][2], const pg8::Unit& u, int wr, int wc, int fr, int fq) const {
;         EPI_LOOP_BEGIN
;             float g[8]; unpack8(*(const u32x4*)((const bf16_t*)(ws + O_GATES) + (size_t)t * 3072 + PASS * 1024 + c0), g);
;             bf16_t* mp = (bf16_t*)(ws + O_HM) + (size_t)t * 1024 + c0;
;             if (PASS > 0) { float pv[8]; unpack8(*(const u32x4*)mp, pv);
; #pragma unroll
;                 for (int e = 0; e < 8; ++e) v[e] = pv[e] + g[e] * v[e];
;             } else {
; #pragma unroll
;                 for (int e = 0; e < 8; ++e) v[e] *= g[e];
;             }
;             *(u32x4*)mp = pack8(v);
;         EPI_LOOP_END
;     }
	v_lshlrev_b32_e32 v158, 16, v182
	v_and_b32_e32 v159, 0xffff0000, v182
	v_lshlrev_b32_e32 v160, 16, v183
	v_and_b32_e32 v161, 0xffff0000, v183
	v_lshlrev_b32_e32 v162, 16, v184
	v_and_b32_e32 v163, 0xffff0000, v184
	v_lshlrev_b32_e32 v164, 16, v185
	v_and_b32_e32 v165, 0xffff0000, v185
	v_pk_mul_f32 v[48:49], v[48:49], v[158:159]
	v_pk_mul_f32 v[50:51], v[50:51], v[160:161]
	v_pk_mul_f32 v[32:33], v[32:33], v[162:163]
	v_pk_mul_f32 v[34:35], v[34:35], v[164:165]
	v_cvt_pk_bf16_f32 v158, v48, v49
	v_cvt_pk_bf16_f32 v159, v50, v51
	v_cvt_pk_bf16_f32 v160, v32, v33
	v_cvt_pk_bf16_f32 v161, v34, v35
	v_add_u32_e32 v209, 0x18100, v155
	global_store_dwordx4 v209, v[158:161], s[20:21]
	v_add_u32_e32 v208, 0x108100, v149
	global_load_dwordx4 v[182:185], v208, s[34:35]
	s_waitcnt vmcnt(6)
	v_lshlrev_b32_e32 v158, 16, v150
	v_and_b32_e32 v159, 0xffff0000, v150
	v_lshlrev_b32_e32 v160, 16, v151
	v_and_b32_e32 v161, 0xffff0000, v151
	v_lshlrev_b32_e32 v162, 16, v152
	v_and_b32_e32 v163, 0xffff0000, v152
	v_lshlrev_b32_e32 v164, 16, v153
	v_and_b32_e32 v165, 0xffff0000, v153
	v_pk_mul_f32 v[28:29], v[28:29], v[158:159]
	v_pk_mul_f32 v[30:31], v[30:31], v[160:161]
	v_pk_mul_f32 v[24:25], v[24:25], v[162:163]
	v_pk_mul_f32 v[26:27], v[26:27], v[164:165]
	v_cvt_pk_bf16_f32 v158, v28, v29
	v_cvt_pk_bf16_f32 v159, v30, v31
	v_cvt_pk_bf16_f32 v160, v24, v25
	v_cvt_pk_bf16_f32 v161, v26, v27
	v_add_u32_e32 v209, 0x40100, v155
	global_store_dwordx4 v209, v[158:161], s[20:21]
	s_nop 1
	s_waitcnt vmcnt(5)
	v_lshlrev_b32_e32 v158, 16, v174
	v_and_b32_e32 v159, 0xffff0000, v174
	v_lshlrev_b32_e32 v160, 16, v175
	v_and_b32_e32 v161, 0xffff0000, v175
	v_lshlrev_b32_e32 v162, 16, v176
	v_and_b32_e32 v163, 0xffff0000, v176
	v_lshlrev_b32_e32 v164, 16, v177
	v_and_b32_e32 v165, 0xffff0000, v177
	v_pk_mul_f32 v[20:21], v[20:21], v[158:159]
	v_pk_mul_f32 v[22:23], v[22:23], v[160:161]
	v_pk_mul_f32 v[16:17], v[16:17], v[162:163]
	v_pk_mul_f32 v[18:19], v[18:19], v[164:165]
	v_cvt_pk_bf16_f32 v158, v20, v21
	v_cvt_pk_bf16_f32 v159, v22, v23
	v_cvt_pk_bf16_f32 v160, v16, v17
	v_cvt_pk_bf16_f32 v161, v18, v19
	v_add_u32_e32 v209, 0x48100, v155
	global_store_dwordx4 v209, v[158:161], s[20:21]
	s_nop 1
	s_waitcnt vmcnt(4)
	v_lshlrev_b32_e32 v158, 16, v178
	v_and_b32_e32 v159, 0xffff0000, v178
	v_lshlrev_b32_e32 v160, 16, v179
	v_and_b32_e32 v161, 0xffff0000, v179
	v_lshlrev_b32_e32 v162, 16, v180
	v_and_b32_e32 v163, 0xffff0000, v180
	v_lshlrev_b32_e32 v164, 16, v181
	v_and_b32_e32 v165, 0xffff0000, v181
	v_pk_mul_f32 v[12:13], v[12:13], v[158:159]
	v_pk_mul_f32 v[14:15], v[14:15], v[160:161]
	v_pk_mul_f32 v[8:9], v[8:9], v[162:163]
	v_pk_mul_f32 v[10:11], v[10:11], v[164:165]
	v_cvt_pk_bf16_f32 v158, v12, v13
	v_cvt_pk_bf16_f32 v159, v14, v15
	v_cvt_pk_bf16_f32 v160, v8, v9
	v_cvt_pk_bf16_f32 v161, v10, v11
	v_add_u32_e32 v209, 0x50100, v155
	global_store_dwordx4 v209, v[158:161], s[20:21]
	s_nop 1
	s_waitcnt vmcnt(3)
	v_lshlrev_b32_e32 v158, 16, v182
	v_and_b32_e32 v159, 0xffff0000, v182
	v_lshlrev_b32_e32 v160, 16, v183
	v_and_b32_e32 v161, 0xffff0000, v183
	v_lshlrev_b32_e32 v162, 16, v184
	v_and_b32_e32 v163, 0xffff0000, v184
	v_lshlrev_b32_e32 v164, 16, v185
	v_and_b32_e32 v165, 0xffff0000, v185
	v_pk_mul_f32 v[4:5], v[4:5], v[158:159]
	v_pk_mul_f32 v[6:7], v[6:7], v[160:161]
	v_pk_mul_f32 v[0:1], v[0:1], v[162:163]
	v_pk_mul_f32 v[2:3], v[2:3], v[164:165]
	v_cvt_pk_bf16_f32 v158, v4, v5
	v_cvt_pk_bf16_f32 v159, v6, v7
	v_cvt_pk_bf16_f32 v160, v0, v1
	v_cvt_pk_bf16_f32 v161, v2, v3
	v_add_u32_e32 v209, 0x58100, v155
	global_store_dwordx4 v209, v[158:161], s[20:21]
	s_nop 1
	s_mov_b64 s[0:1], -1
	s_and_b64 vcc, exec, s[38:39]
	s_cbranch_vccnz .LBB0_262
	s_andn2_b64 vcc, exec, s[16:17]
	s_cbranch_vccnz .LBB0_261
	s_barrier
	s_branch .LBB0_261

; __device__ __forceinline__ u32x4 pack8(const float* v) { u32x4 w; w.x = pk2(v[0], v[1]); w.y = pk2(v[2], v[3]); w.z = pk2(v[4], v[5]); w.w = pk2(v[6], v[7]); return w; }
; __device__ __forceinline__ void unpack8(u32x4 w, float* v) { v[0] = bflo(w.x); v[1] = bfhi(w.x); v[2] = bflo(w.y); v[3] = bfhi(w.y); v[4] = bflo(w.z); v[5] = bfhi(w.z); v[6] = bflo(w.w); v[7] = bfhi(w.w); }
; #define EPI_LOOP_END asm volatile("" ::: "memory"); } }
;     __device__ __forceinline__ void operator()(const f32x4 (&acc)[2][2][4][2], const pg8::Unit& u, int wr, int wc, int fr, int fq) const {
;         EPI_LOOP_BEGIN
;             float g[8]; unpack8(*(const u32x4*)((const bf16_t*)(ws + O_GATES) + (size_t)t * 3072 + PASS * 1024 + c0), g);
;             bf16_t* mp = (bf16_t*)(ws + O_HM) + (size_t)t * 1024 + c0;
;             if (PASS > 0) { float pv[8]; unpack8(*(const u32x4*)mp, pv);
; #pragma unroll
;                 for (int e = 0; e < 8; ++e) v[e] = pv[e] + g[e] * v[e];
;             } else {
; #pragma unroll
;                 for (int e = 0; e < 8; ++e) v[e] *= g[e];
;             }
;             *(u32x4*)mp = pack8(v);
;         EPI_LOOP_END
;     }
.LBB0_296:
	s_lshl_b32 s0, s68, 8
	v_mov_b32_e32 v148, v37
	v_mov_b32_e32 v149, v41
	s_or_b32 s0, s0, s60
	v_mov_b64_e32 v[158:159], s[4:5]
	v_lshl_add_u32 v150, v148, 3, s0
	s_lshl_b32 s0, s69, 8
	s_add_i32 s0, s0, s59
	v_add_u32_e32 v156, s0, v149
	v_mul_u32_u24_e32 v148, 0x1800, v156
	v_lshl_add_u32 v148, v150, 1, v148
	v_lshlrev_b32_e32 v149, 11, v156
	v_lshl_add_u32 v149, v150, 1, v149
	s_add_u32 s18, s4, 0x12870800
	s_addc_u32 s19, s5, 0
	global_load_dwordx4 v[152:155], v148, s[18:19]
	global_load_dwordx4 v[190:193], v149, s[20:21]
	v_add_u32_e32 v151, 0x18000, v148
	global_load_dwordx4 v[178:181], v151, s[18:19]
	v_add_u32_e32 v157, 0x8000, v149
	global_load_dwordx4 v[194:197], v157, s[20:21]
	v_add_u32_e32 v151, 0x30000, v148
	global_load_dwordx4 v[182:185], v151, s[18:19]
	v_add_u32_e32 v157, 0x10000, v149
	global_load_dwordx4 v[204:207], v157, s[20:21]
	v_add_u32_e32 v151, 0x48000, v148
	global_load_dwordx4 v[186:189], v151, s[18:19]
	v_add_u32_e32 v157, 0x18000, v149
	global_load_dwordx4 v[208:211], v157, s[20:21]
	s_waitcnt vmcnt(6)
	v_lshlrev_b32_e32 v162, 16, v152
	v_and_b32_e32 v163, 0xffff0000, v152
	v_lshlrev_b32_e32 v164, 16, v153
	v_and_b32_e32 v165, 0xffff0000, v153
	v_lshlrev_b32_e32 v166, 16, v154
	v_and_b32_e32 v167, 0xffff0000, v154
	v_lshlrev_b32_e32 v168, 16, v155
	v_and_b32_e32 v169, 0xffff0000, v155
	v_lshlrev_b32_e32 v170, 16, v190
	v_and_b32_e32 v171, 0xffff0000, v190
	v_lshlrev_b32_e32 v172, 16, v191
	v_and_b32_e32 v173, 0xffff0000, v191
	v_lshlrev_b32_e32 v174, 16, v192
	v_and_b32_e32 v175, 0xffff0000, v192
	v_lshlrev_b32_e32 v176, 16, v193
	v_and_b32_e32 v177, 0xffff0000, v193
	v_pk_fma_f32 v[136:137], v[136:137], v[162:163], v[170:171]
	v_pk_fma_f32 v[138:139], v[138:139], v[164:165], v[172:173]
	v_pk_fma_f32 v[132:133], v[132:133], v[166:167], v[174:175]
	v_pk_fma_f32 v[134:135], v[134:135], v[168:169], v[176:177]
	v_cvt_pk_bf16_f32 v162, v136, v137
	v_cvt_pk_bf16_f32 v163, v138, v139
	v_cvt_pk_bf16_f32 v164, v132, v133
	v_cvt_pk_bf16_f32 v165, v134, v135
	global_store_dwordx4 v149, v[162:165], s[20:21]
	v_add_u32_e32 v151, 0xc0000, v148
	global_load_dwordx4 v[152:155], v151, s[18:19]
	v_add_u32_e32 v157, 0x40000, v149
	global_load_dwordx4 v[190:193], v157, s[20:21]
	s_waitcnt vmcnt(7)
	v_lshlrev_b32_e32 v162, 16, v178
	v_and_b32_e32 v163, 0xffff0000, v178
	v_lshlrev_b32_e32 v164, 16, v179
	v_and_b32_e32 v165, 0xffff0000, v179
	v_lshlrev_b32_e32 v166, 16, v180
	v_and_b32_e32 v167, 0xffff0000, v180
	v_lshlrev_b32_e32 v168, 16, v181
	v_and_b32_e32 v169, 0xffff0000, v181
	v_lshlrev_b32_e32 v170, 16, v194
	v_and_b32_e32 v171, 0xffff0000, v194
	v_lshlrev_b32_e32 v172, 16, v195
	v_and_b32_e32 v173, 0xffff0000, v195
	v_lshlrev_b32_e32 v174, 16, v196
	v_and_b32_e32 v175, 0xffff0000, v196
	v_lshlrev_b32_e32 v176, 16, v197
	v_and_b32_e32 v177, 0xffff0000, v197
	v_pk_fma_f32 v[128:129], v[128:129], v[162:163], v[170:171]
	v_pk_fma_f32 v[130:131], v[130:131], v[164:165], v[172:173]
	v_pk_fma_f32 v[124:125], v[124:125], v[166:167], v[174:175]
	v_pk_fma_f32 v[126:127], v[126:127], v[168:169], v[176:177]
	v_cvt_pk_bf16_f32 v162, v128, v129
	v_cvt_pk_bf16_f32 v163, v130, v131
	v_cvt_pk_bf16_f32 v164, v124, v125
	v_cvt_pk_bf16_f32 v165, v126, v127
	v_add_u32_e32 v157, 0x8000, v149
	global_store_dwordx4 v157, v[162:165], s[20:21]
	v_add_u32_e32 v151, 0xd8000, v148
	global_load_dwordx4 v[178:181], v151, s[18:19]
	v_add_u32_e32 v157, 0x48000, v149
	global_load_dwordx4 v[194:197], v157, s[20:21]
	s_waitcnt vmcnt(8)
	v_lshlrev_b32_e32 v162, 16, v182
	v_and_b32_e32 v163, 0xffff0000, v182
	v_lshlrev_b32_e32 v164, 16, v183
	v_and_b32_e32 v165, 0xffff0000, v183
	v_lshlrev_b32_e32 v166, 16, v184
	v_and_b32_e32 v167, 0xffff0000, v184
	v_lshlrev_b32_e32 v168, 16, v185
	v_and_b32_e32 v169, 0xffff0000, v185
	v_lshlrev_b32_e32 v170, 16, v204
	v_and_b32_e32 v171, 0xffff0000, v204
	v_lshlrev_b32_e32 v172, 16, v205
	v_and_b32_e32 v173, 0xffff0000, v205
	v_lshlrev_b32_e32 v174, 16, v206
	v_and_b32_e32 v175, 0xffff0000, v206
	v_lshlrev_b32_e32 v176, 16, v207
	v_and_b32_e32 v177, 0xffff0000, v207
	v_pk_fma_f32 v[120:121], v[120:121], v[162:163], v[170:171]
	v_pk_fma_f32 v[122:123], v[122:123], v[164:165], v[172:173]
	v_pk_fma_f32 v[116:117], v[116:117], v[166:167], v[174:175]
	v_pk_fma_f32 v[118:119], v[118:119], v[168:169], v[176:177]
	v_cvt_pk_bf16_f32 v162, v120, v121
	v_cvt_pk_bf16_f32 v163, v122, v123
	v_cvt_pk_bf16_f32 v164, v116, v117
	v_cvt_pk_bf16_f32 v165, v118, v119
	v_add_u32_e32 v157, 0x10000, v149
	global_store_dwordx4 v157, v[162:165], s[20:21]
	v_add_u32_e32 v151, 0xf0000, v148
	global_load_dwordx4 v[182:185], v151, s[18:19]
	v_add_u32_e32 v157, 0x50000, v149
	global_load_dwordx4 v[204:207], v157, s[20:21]
	s_waitcnt vmcnt(9)
	v_lshlrev_b32_e32 v162, 16, v186
	v_and_b32_e32 v163, 0xffff0000, v186
	v_lshlrev_b32_e32 v164, 16, v187
	v_and_b32_e32 v165, 0xffff0000, v187
	v_lshlrev_b32_e32 v166, 16, v188
	v_and_b32_e32 v167, 0xffff0000, v188
	v_lshlrev_b32_e32 v168, 16, v189
	v_and_b32_e32 v169, 0xffff0000, v189
	v_lshlrev_b32_e32 v170, 16, v208
	v_and_b32_e32 v171, 0xffff0000, v208
	v_lshlrev_b32_e32 v172, 16, v209
	v_and_b32_e32 v173, 0xffff0000, v209
	v_lshlrev_b32_e32 v174, 16, v210
	v_and_b32_e32 v175, 0xffff0000, v210
	v_lshlrev_b32_e32 v176, 16, v211
	v_and_b32_e32 v177, 0xffff0000, v211
	v_pk_fma_f32 v[112:113], v[112:113], v[162:163], v[170:171]
	v_pk_fma_f32 v[114:115], v[114:115], v[164:165], v[172:173]
	v_pk_fma_f32 v[108:109], v[108:109], v[166:167], v[174:175]
	v_pk_fma_f32 v[110:111], v[110:111], v[168:169], v[176:177]
	v_cvt_pk_bf16_f32 v162, v112, v113
	v_cvt_pk_bf16_f32 v163, v114, v115
	v_cvt_pk_bf16_f32 v164, v108, v109
	v_cvt_pk_bf16_f32 v165, v110, v111
	v_add_u32_e32 v157, 0x18000, v149
	global_store_dwordx4 v157, v[162:165], s[20:21]
	v_add_u32_e32 v151, 0x108000, v148
	global_load_dwordx4 v[186:189], v151, s[18:19]
	v_add_u32_e32 v157, 0x58000, v149
	global_load_dwordx4 v[208:211], v157, s[20:21]
	s_waitcnt vmcnt(9)
; __device__ __forceinline__ u32x4 pack8(const float* v) { u32x4 w; w.x = pk2(v[0], v[1]); w.y = pk2(v[2], v[3]); w.z = pk2(v[4], v[5]); w.w = pk2(v[6], v[7]); return w; }
; __device__ __forceinline__ void unpack8(u32x4 w, float* v) { v[0] = bflo(w.x); v[1] = bfhi(w.x); v[2] = bflo(w.y); v[3] = bfhi(w.y); v[4] = bflo(w.z); v[5] = bfhi(w.z); v[6] = bflo(w.w); v[7] = bfhi(w.w); }
; #define EPI_LOOP_END asm volatile("" ::: "memory"); } }
;     __device__ __forceinline__ void operator()(const f32x4 (&acc)[2][2][4][2], const pg8::Unit& u, int wr, int wc, int fr, int fq) const {
;         EPI_LOOP_BEGIN
;             float g[8]; unpack8(*(const u32x4*)((const bf16_t*)(ws + O_GATES) + (size_t)t * 3072 + PASS * 1024 + c0), g);
;             bf16_t* mp = (bf16_t*)(ws + O_HM) + (size_t)t * 1024 + c0;
;             if (PASS > 0) { float pv[8]; unpack8(*(const u32x4*)mp, pv);
; #pragma unroll
;                 for (int e = 0; e < 8; ++e) v[e] = pv[e] + g[e] * v[e];
;             } else {
; #pragma unroll
;                 for (int e = 0; e < 8; ++e) v[e] *= g[e];
;             }
;             *(u32x4*)mp = pack8(v);
;         EPI_LOOP_END
;     }
	v_lshlrev_b32_e32 v162, 16, v152
	v_and_b32_e32 v163, 0xffff0000, v152
	v_lshlrev_b32_e32 v164, 16, v153
	v_and_b32_e32 v165, 0xffff0000, v153
	v_lshlrev_b32_e32 v166, 16, v154
	v_and_b32_e32 v167, 0xffff0000, v154
	v_lshlrev_b32_e32 v168, 16, v155
	v_and_b32_e32 v169, 0xffff0000, v155
	v_lshlrev_b32_e32 v170, 16, v190
	v_and_b32_e32 v171, 0xffff0000, v190
	v_lshlrev_b32_e32 v172, 16, v191
	v_and_b32_e32 v173, 0xffff0000, v191
	v_lshlrev_b32_e32 v174, 16, v192
	v_and_b32_e32 v175, 0xffff0000, v192
	v_lshlrev_b32_e32 v176, 16, v193
	v_and_b32_e32 v177, 0xffff0000, v193
	v_pk_fma_f32 v[104:105], v[104:105], v[162:163], v[170:171]
	v_pk_fma_f32 v[106:107], v[106:107], v[164:165], v[172:173]
	v_pk_fma_f32 v[100:101], v[100:101], v[166:167], v[174:175]
	v_pk_fma_f32 v[102:103], v[102:103], v[168:169], v[176:177]
	v_cvt_pk_bf16_f32 v162, v104, v105
	v_cvt_pk_bf16_f32 v163, v106, v107
	v_cvt_pk_bf16_f32 v164, v100, v101
	v_cvt_pk_bf16_f32 v165, v102, v103
	v_add_u32_e32 v157, 0x40000, v149
	global_store_dwordx4 v157, v[162:165], s[20:21]
	v_add_u32_e32 v151, 0x100, v148
	global_load_dwordx4 v[152:155], v151, s[18:19]
	v_add_u32_e32 v157, 0x100, v149
	global_load_dwordx4 v[190:193], v157, s[20:21]
	s_waitcnt vmcnt(9)
	v_lshlrev_b32_e32 v162, 16, v178
	v_and_b32_e32 v163, 0xffff0000, v178
	v_lshlrev_b32_e32 v164, 16, v179
	v_and_b32_e32 v165, 0xffff0000, v179
	v_lshlrev_b32_e32 v166, 16, v180
	v_and_b32_e32 v167, 0xffff0000, v180
	v_lshlrev_b32_e32 v168, 16, v181
	v_and_b32_e32 v169, 0xffff0000, v181
	v_lshlrev_b32_e32 v170, 16, v194
	v_and_b32_e32 v171, 0xffff0000, v194
	v_lshlrev_b32_e32 v172, 16, v195
	v_and_b32_e32 v173, 0xffff0000, v195
	v_lshlrev_b32_e32 v174, 16, v196
	v_and_b32_e32 v175, 0xffff0000, v196
	v_lshlrev_b32_e32 v176, 16, v197
	v_and_b32_e32 v177, 0xffff0000, v197
	v_pk_fma_f32 v[96:97], v[96:97], v[162:163], v[170:171]
	v_pk_fma_f32 v[98:99], v[98:99], v[164:165], v[172:173]
	v_pk_fma_f32 v[92:93], v[92:93], v[166:167], v[174:175]
	v_pk_fma_f32 v[94:95], v[94:95], v[168:169], v[176:177]
	v_cvt_pk_bf16_f32 v162, v96, v97
	v_cvt_pk_bf16_f32 v163, v98, v99
	v_cvt_pk_bf16_f32 v164, v92, v93
	v_cvt_pk_bf16_f32 v165, v94, v95
	v_add_u32_e32 v157, 0x48000, v149
	global_store_dwordx4 v157, v[162:165], s[20:21]
	v_add_u32_e32 v151, 0x18100, v148
	global_load_dwordx4 v[178:181], v151, s[18:19]
	v_add_u32_e32 v157, 0x8100, v149
	global_load_dwordx4 v[194:197], v157, s[20:21]
	s_waitcnt vmcnt(9)
	v_lshlrev_b32_e32 v162, 16, v182
	v_and_b32_e32 v163, 0xffff0000, v182
	v_lshlrev_b32_e32 v164, 16, v183
	v_and_b32_e32 v165, 0xffff0000, v183
	v_lshlrev_b32_e32 v166, 16, v184
	v_and_b32_e32 v167, 0xffff0000, v184
	v_lshlrev_b32_e32 v168, 16, v185
	v_and_b32_e32 v169, 0xffff0000, v185
	v_lshlrev_b32_e32 v170, 16, v204
	v_and_b32_e32 v171, 0xffff0000, v204
	v_lshlrev_b32_e32 v172, 16, v205
	v_and_b32_e32 v173, 0xffff0000, v205
	v_lshlrev_b32_e32 v174, 16, v206
	v_and_b32_e32 v175, 0xffff0000, v206
	v_lshlrev_b32_e32 v176, 16, v207
	v_and_b32_e32 v177, 0xffff0000, v207
	v_pk_fma_f32 v[88:89], v[88:89], v[162:163], v[170:171]
	v_pk_fma_f32 v[90:91], v[90:91], v[164:165], v[172:173]
	v_pk_fma_f32 v[84:85], v[84:85], v[166:167], v[174:175]
	v_pk_fma_f32 v[86:87], v[86:87], v[168:169], v[176:177]
	v_cvt_pk_bf16_f32 v162, v88, v89
	v_cvt_pk_bf16_f32 v163, v90, v91
	v_cvt_pk_bf16_f32 v164, v84, v85
	v_cvt_pk_bf16_f32 v165, v86, v87
	v_add_u32_e32 v157, 0x50000, v149
	global_store_dwordx4 v157, v[162:165], s[20:21]
	v_add_u32_e32 v151, 0x30100, v148
	global_load_dwordx4 v[182:185], v151, s[18:19]
	v_add_u32_e32 v157, 0x10100, v149
	global_load_dwordx4 v[204:207], v157, s[20:21]
	s_waitcnt vmcnt(9)
	v_lshlrev_b32_e32 v162, 16, v186
	v_and_b32_e32 v163, 0xffff0000, v186
	v_lshlrev_b32_e32 v164, 16, v187
	v_and_b32_e32 v165, 0xffff0000, v187
	v_lshlrev_b32_e32 v166, 16, v188
	v_and_b32_e32 v167, 0xffff0000, v188
	v_lshlrev_b32_e32 v168, 16, v189
	v_and_b32_e32 v169, 0xffff0000, v189
	v_lshlrev_b32_e32 v170, 16, v208
	v_and_b32_e32 v171, 0xffff0000, v208
	v_lshlrev_b32_e32 v172, 16, v209
	v_and_b32_e32 v173, 0xffff0000, v209
	v_lshlrev_b32_e32 v174, 16, v210
	v_and_b32_e32 v175, 0xffff0000, v210
	v_lshlrev_b32_e32 v176, 16, v211
	v_and_b32_e32 v177, 0xffff0000, v211
	v_pk_fma_f32 v[80:81], v[80:81], v[162:163], v[170:171]
	v_pk_fma_f32 v[82:83], v[82:83], v[164:165], v[172:173]
	v_pk_fma_f32 v[76:77], v[76:77], v[166:167], v[174:175]
	v_pk_fma_f32 v[78:79], v[78:79], v[168:169], v[176:177]
	v_cvt_pk_bf16_f32 v162, v80, v81
	v_cvt_pk_bf16_f32 v163, v82, v83
	v_cvt_pk_bf16_f32 v164, v76, v77
	v_cvt_pk_bf16_f32 v165, v78, v79
	v_add_u32_e32 v157, 0x58000, v149
	global_store_dwordx4 v157, v[162:165], s[20:21]
	v_add_u32_e32 v151, 0x48100, v148
	global_load_dwordx4 v[186:189], v151, s[18:19]
	v_add_u32_e32 v157, 0x18100, v149
	global_load_dwordx4 v[208:211], v157, s[20:21]
	s_waitcnt vmcnt(9)
	v_lshlrev_b32_e32 v162, 16, v152
	v_and_b32_e32 v163, 0xffff0000, v152
	v_lshlrev_b32_e32 v164, 16, v153
	v_and_b32_e32 v165, 0xffff0000, v153
	v_lshlrev_b32_e32 v166, 16, v154
	v_and_b32_e32 v167, 0xffff0000, v154
	v_lshlrev_b32_e32 v168, 16, v155
	v_and_b32_e32 v169, 0xffff0000, v155
	v_lshlrev_b32_e32 v170, 16, v190
	v_and_b32_e32 v171, 0xffff0000, v190
	v_lshlrev_b32_e32 v172, 16, v191
	v_and_b32_e32 v173, 0xffff0000, v191
	v_lshlrev_b32_e32 v174, 16, v192
	v_and_b32_e32 v175, 0xffff0000, v192
	v_lshlrev_b32_e32 v176, 16, v193
	v_and_b32_e32 v177, 0xffff0000, v193
	v_pk_fma_f32 v[72:73], v[72:73], v[162:163], v[170:171]
	v_pk_fma_f32 v[74:75], v[74:75], v[164:165], v[172:173]
	v_pk_fma_f32 v[68:69], v[68:69], v[166:167], v[174:175]
	v_pk_fma_f32 v[70:71], v[70:71], v[168:169], v[176:177]
	v_cvt_pk_bf16_f32 v162, v72, v73
	v_cvt_pk_bf16_f32 v163, v74, v75
	v_cvt_pk_bf16_f32 v164, v68, v69
	v_cvt_pk_bf16_f32 v165, v70, v71
	v_add_u32_e32 v157, 0x100, v149
	global_store_dwordx4 v157, v[162:165], s[20:21]
	v_add_u32_e32 v151, 0xc0100, v148
	global_load_dwordx4 v[152:155], v151, s[18:19]
	v_add_u32_e32 v157, 0x40100, v149
	global_load_dwordx4 v[190:193], v157, s[20:21]
	s_waitcnt vmcnt(9)
; __device__ __forceinline__ u32x4 pack8(const float* v) { u32x4 w; w.x = pk2(v[0], v[1]); w.y = pk2(v[2], v[3]); w.z = pk2(v[4], v[5]); w.w = pk2(v[6], v[7]); return w; }
; __device__ __forceinline__ void unpack8(u32x4 w, float* v) { v[0] = bflo(w.x); v[1] = bfhi(w.x); v[2] = bflo(w.y); v[3] = bfhi(w.y); v[4] = bflo(w.z); v[5] = bfhi(w.z); v[6] = bflo(w.w); v[7] = bfhi(w.w); }
; #define EPI_LOOP_END asm volatile("" ::: "memory"); } }
;     __device__ __forceinline__ void operator()(const f32x4 (&acc)[2][2][4][2], const pg8::Unit& u, int wr, int wc, int fr, int fq) const {
;         EPI_LOOP_BEGIN
;             float g[8]; unpack8(*(const u32x4*)((const bf16_t*)(ws + O_GATES) + (size_t)t * 3072 + PASS * 1024 + c0), g);
;             bf16_t* mp = (bf16_t*)(ws + O_HM) + (size_t)t * 1024 + c0;
;             if (PASS > 0) { float pv[8]; unpack8(*(const u32x4*)mp, pv);
; #pragma unroll
;                 for (int e = 0; e < 8; ++e) v[e] = pv[e] + g[e] * v[e];
;             } else {
; #pragma unroll
;                 for (int e = 0; e < 8; ++e) v[e] *= g[e];
;             }
;             *(u32x4*)mp = pack8(v);
;         EPI_LOOP_END
;     }
	v_lshlrev_b32_e32 v162, 16, v178
	v_and_b32_e32 v163, 0xffff0000, v178
	v_lshlrev_b32_e32 v164, 16, v179
	v_and_b32_e32 v165, 0xffff0000, v179
	v_lshlrev_b32_e32 v166, 16, v180
	v_and_b32_e32 v167, 0xffff0000, v180
	v_lshlrev_b32_e32 v168, 16, v181
	v_and_b32_e32 v169, 0xffff0000, v181
	v_lshlrev_b32_e32 v170, 16, v194
	v_and_b32_e32 v171, 0xffff0000, v194
	v_lshlrev_b32_e32 v172, 16, v195
	v_and_b32_e32 v173, 0xffff0000, v195
	v_lshlrev_b32_e32 v174, 16, v196
	v_and_b32_e32 v175, 0xffff0000, v196
	v_lshlrev_b32_e32 v176, 16, v197
	v_and_b32_e32 v177, 0xffff0000, v197
	v_pk_fma_f32 v[64:65], v[64:65], v[162:163], v[170:171]
	v_pk_fma_f32 v[66:67], v[66:67], v[164:165], v[172:173]
	v_pk_fma_f32 v[60:61], v[60:61], v[166:167], v[174:175]
	v_pk_fma_f32 v[62:63], v[62:63], v[168:169], v[176:177]
	v_cvt_pk_bf16_f32 v162, v64, v65
	v_cvt_pk_bf16_f32 v163, v66, v67
	v_cvt_pk_bf16_f32 v164, v60, v61
	v_cvt_pk_bf16_f32 v165, v62, v63
	v_add_u32_e32 v157, 0x8100, v149
	global_store_dwordx4 v157, v[162:165], s[20:21]
	v_add_u32_e32 v151, 0xd8100, v148
	global_load_dwordx4 v[178:181], v151, s[18:19]
	v_add_u32_e32 v157, 0x48100, v149
	global_load_dwordx4 v[194:197], v157, s[20:21]
	s_waitcnt vmcnt(9)
	v_lshlrev_b32_e32 v162, 16, v182
	v_and_b32_e32 v163, 0xffff0000, v182
	v_lshlrev_b32_e32 v164, 16, v183
	v_and_b32_e32 v165, 0xffff0000, v183
	v_lshlrev_b32_e32 v166, 16, v184
	v_and_b32_e32 v167, 0xffff0000, v184
	v_lshlrev_b32_e32 v168, 16, v185
	v_and_b32_e32 v169, 0xffff0000, v185
	v_lshlrev_b32_e32 v170, 16, v204
	v_and_b32_e32 v171, 0xffff0000, v204
	v_lshlrev_b32_e32 v172, 16, v205
	v_and_b32_e32 v173, 0xffff0000, v205
	v_lshlrev_b32_e32 v174, 16, v206
	v_and_b32_e32 v175, 0xffff0000, v206
	v_lshlrev_b32_e32 v176, 16, v207
	v_and_b32_e32 v177, 0xffff0000, v207
	v_pk_fma_f32 v[56:57], v[56:57], v[162:163], v[170:171]
	v_pk_fma_f32 v[58:59], v[58:59], v[164:165], v[172:173]
	v_pk_fma_f32 v[52:53], v[52:53], v[166:167], v[174:175]
	v_pk_fma_f32 v[54:55], v[54:55], v[168:169], v[176:177]
	v_cvt_pk_bf16_f32 v162, v56, v57
	v_cvt_pk_bf16_f32 v163, v58, v59
	v_cvt_pk_bf16_f32 v164, v52, v53
	v_cvt_pk_bf16_f32 v165, v54, v55
	v_add_u32_e32 v157, 0x10100, v149
	global_store_dwordx4 v157, v[162:165], s[20:21]
	v_add_u32_e32 v151, 0xf0100, v148
	global_load_dwordx4 v[182:185], v151, s[18:19]
	v_add_u32_e32 v157, 0x50100, v149
	global_load_dwordx4 v[204:207], v157, s[20:21]
	s_waitcnt vmcnt(9)
	v_lshlrev_b32_e32 v162, 16, v186
	v_and_b32_e32 v163, 0xffff0000, v186
	v_lshlrev_b32_e32 v164, 16, v187
	v_and_b32_e32 v165, 0xffff0000, v187
	v_lshlrev_b32_e32 v166, 16, v188
	v_and_b32_e32 v167, 0xffff0000, v188
	v_lshlrev_b32_e32 v168, 16, v189
	v_and_b32_e32 v169, 0xffff0000, v189
	v_lshlrev_b32_e32 v170, 16, v208
	v_and_b32_e32 v171, 0xffff0000, v208
	v_lshlrev_b32_e32 v172, 16, v209
	v_and_b32_e32 v173, 0xffff0000, v209
	v_lshlrev_b32_e32 v174, 16, v210
	v_and_b32_e32 v175, 0xffff0000, v210
	v_lshlrev_b32_e32 v176, 16, v211
	v_and_b32_e32 v177, 0xffff0000, v211
	v_pk_fma_f32 v[48:49], v[48:49], v[162:163], v[170:171]
	v_pk_fma_f32 v[50:51], v[50:51], v[164:165], v[172:173]
	v_pk_fma_f32 v[32:33], v[32:33], v[166:167], v[174:175]
	v_pk_fma_f32 v[34:35], v[34:35], v[168:169], v[176:177]
	v_cvt_pk_bf16_f32 v162, v48, v49
	v_cvt_pk_bf16_f32 v163, v50, v51
	v_cvt_pk_bf16_f32 v164, v32, v33
	v_cvt_pk_bf16_f32 v165, v34, v35
	v_add_u32_e32 v157, 0x18100, v149
	global_store_dwordx4 v157, v[162:165], s[20:21]
	v_add_u32_e32 v151, 0x108100, v148
	global_load_dwordx4 v[186:189], v151, s[18:19]
	v_add_u32_e32 v157, 0x58100, v149
	global_load_dwordx4 v[208:211], v157, s[20:21]
	s_waitcnt vmcnt(9)
; __device__ __forceinline__ u32x4 pack8(const float* v) { u32x4 w; w.x = pk2(v[0], v[1]); w.y = pk2(v[2], v[3]); w.z = pk2(v[4], v[5]); w.w = pk2(v[6], v[7]); return w; }
; __device__ __forceinline__ void unpack8(u32x4 w, float* v) { v[0] = bflo(w.x); v[1] = bfhi(w.x); v[2] = bflo(w.y); v[3] = bfhi(w.y); v[4] = bflo(w.z); v[5] = bfhi(w.z); v[6] = bflo(w.w); v[7] = bfhi(w.w); }
; #define EPI_LOOP_END asm volatile("" ::: "memory"); } }
;     __device__ __forceinline__ void operator()(const f32x4 (&acc)[2][2][4][2], const pg8::Unit& u, int wr, int wc, int fr, int fq) const {
;         EPI_LOOP_BEGIN
;             float g[8]; unpack8(*(const u32x4*)((const bf16_t*)(ws + O_GATES) + (size_t)t * 3072 + PASS * 1024 + c0), g);
;             bf16_t* mp = (bf16_t*)(ws + O_HM) + (size_t)t * 1024 + c0;
;             if (PASS > 0) { float pv[8]; unpack8(*(const u32x4*)mp, pv);
; #pragma unroll
;                 for (int e = 0; e < 8; ++e) v[e] = pv[e] + g[e] * v[e];
;             } else {
; #pragma unroll
;                 for (int e = 0; e < 8; ++e) v[e] *= g[e];
;             }
;             *(u32x4*)mp = pack8(v);
;         EPI_LOOP_END
;     }
	v_lshlrev_b32_e32 v162, 16, v152
	v_and_b32_e32 v163, 0xffff0000, v152
	v_lshlrev_b32_e32 v164, 16, v153
	v_and_b32_e32 v165, 0xffff0000, v153
	v_lshlrev_b32_e32 v166, 16, v154
	v_and_b32_e32 v167, 0xffff0000, v154
	v_lshlrev_b32_e32 v168, 16, v155
	v_and_b32_e32 v169, 0xffff0000, v155
	v_lshlrev_b32_e32 v170, 16, v190
	v_and_b32_e32 v171, 0xffff0000, v190
	v_lshlrev_b32_e32 v172, 16, v191
	v_and_b32_e32 v173, 0xffff0000, v191
	v_lshlrev_b32_e32 v174, 16, v192
	v_and_b32_e32 v175, 0xffff0000, v192
	v_lshlrev_b32_e32 v176, 16, v193
	v_and_b32_e32 v177, 0xffff0000, v193
	v_pk_fma_f32 v[28:29], v[28:29], v[162:163], v[170:171]
	v_pk_fma_f32 v[30:31], v[30:31], v[164:165], v[172:173]
	v_pk_fma_f32 v[24:25], v[24:25], v[166:167], v[174:175]
	v_pk_fma_f32 v[26:27], v[26:27], v[168:169], v[176:177]
	v_cvt_pk_bf16_f32 v162, v28, v29
	v_cvt_pk_bf16_f32 v163, v30, v31
	v_cvt_pk_bf16_f32 v164, v24, v25
	v_cvt_pk_bf16_f32 v165, v26, v27
	v_add_u32_e32 v157, 0x40100, v149
	global_store_dwordx4 v157, v[162:165], s[20:21]
	s_nop 1
	s_waitcnt vmcnt(7)
	v_lshlrev_b32_e32 v162, 16, v178
	v_and_b32_e32 v163, 0xffff0000, v178
	v_lshlrev_b32_e32 v164, 16, v179
	v_and_b32_e32 v165, 0xffff0000, v179
	v_lshlrev_b32_e32 v166, 16, v180
	v_and_b32_e32 v167, 0xffff0000, v180
	v_lshlrev_b32_e32 v168, 16, v181
	v_and_b32_e32 v169, 0xffff0000, v181
	v_lshlrev_b32_e32 v170, 16, v194
	v_and_b32_e32 v171, 0xffff0000, v194
	v_lshlrev_b32_e32 v172, 16, v195
	v_and_b32_e32 v173, 0xffff0000, v195
	v_lshlrev_b32_e32 v174, 16, v196
	v_and_b32_e32 v175, 0xffff0000, v196
	v_lshlrev_b32_e32 v176, 16, v197
	v_and_b32_e32 v177, 0xffff0000, v197
	v_pk_fma_f32 v[20:21], v[20:21], v[162:163], v[170:171]
	v_pk_fma_f32 v[22:23], v[22:23], v[164:165], v[172:173]
	v_pk_fma_f32 v[16:17], v[16:17], v[166:167], v[174:175]
	v_pk_fma_f32 v[18:19], v[18:19], v[168:169], v[176:177]
	v_cvt_pk_bf16_f32 v162, v20, v21
	v_cvt_pk_bf16_f32 v163, v22, v23
	v_cvt_pk_bf16_f32 v164, v16, v17
	v_cvt_pk_bf16_f32 v165, v18, v19
	v_add_u32_e32 v157, 0x48100, v149
	global_store_dwordx4 v157, v[162:165], s[20:21]
	s_nop 1
	s_waitcnt vmcnt(5)
	v_lshlrev_b32_e32 v162, 16, v182
	v_and_b32_e32 v163, 0xffff0000, v182
	v_lshlrev_b32_e32 v164, 16, v183
	v_and_b32_e32 v165, 0xffff0000, v183
	v_lshlrev_b32_e32 v166, 16, v184
	v_and_b32_e32 v167, 0xffff0000, v184
	v_lshlrev_b32_e32 v168, 16, v185
	v_and_b32_e32 v169, 0xffff0000, v185
	v_lshlrev_b32_e32 v170, 16, v204
	v_and_b32_e32 v171, 0xffff0000, v204
	v_lshlrev_b32_e32 v172, 16, v205
	v_and_b32_e32 v173, 0xffff0000, v205
	v_lshlrev_b32_e32 v174, 16, v206
	v_and_b32_e32 v175, 0xffff0000, v206
	v_lshlrev_b32_e32 v176, 16, v207
	v_and_b32_e32 v177, 0xffff0000, v207
	v_pk_fma_f32 v[12:13], v[12:13], v[162:163], v[170:171]
	v_pk_fma_f32 v[14:15], v[14:15], v[164:165], v[172:173]
	v_pk_fma_f32 v[8:9], v[8:9], v[166:167], v[174:175]
	v_pk_fma_f32 v[10:11], v[10:11], v[168:169], v[176:177]
	v_cvt_pk_bf16_f32 v162, v12, v13
	v_cvt_pk_bf16_f32 v163, v14, v15
	v_cvt_pk_bf16_f32 v164, v8, v9
	v_cvt_pk_bf16_f32 v165, v10, v11
	v_add_u32_e32 v157, 0x50100, v149
	global_store_dwordx4 v157, v[162:165], s[20:21]
	s_nop 1
	s_waitcnt vmcnt(3)
	v_lshlrev_b32_e32 v162, 16, v186
	v_and_b32_e32 v163, 0xffff0000, v186
	v_lshlrev_b32_e32 v164, 16, v187
	v_and_b32_e32 v165, 0xffff0000, v187
	v_lshlrev_b32_e32 v166, 16, v188
	v_and_b32_e32 v167, 0xffff0000, v188
	v_lshlrev_b32_e32 v168, 16, v189
	v_and_b32_e32 v169, 0xffff0000, v189
	v_lshlrev_b32_e32 v170, 16, v208
	v_and_b32_e32 v171, 0xffff0000, v208
	v_lshlrev_b32_e32 v172, 16, v209
	v_and_b32_e32 v173, 0xffff0000, v209
	v_lshlrev_b32_e32 v174, 16, v210
	v_and_b32_e32 v175, 0xffff0000, v210
	v_lshlrev_b32_e32 v176, 16, v211
	v_and_b32_e32 v177, 0xffff0000, v211
	v_pk_fma_f32 v[4:5], v[4:5], v[162:163], v[170:171]
	v_pk_fma_f32 v[6:7], v[6:7], v[164:165], v[172:173]
	v_pk_fma_f32 v[0:1], v[0:1], v[166:167], v[174:175]
	v_pk_fma_f32 v[2:3], v[2:3], v[168:169], v[176:177]
	v_cvt_pk_bf16_f32 v162, v4, v5
	v_cvt_pk_bf16_f32 v163, v6, v7
	v_cvt_pk_bf16_f32 v164, v0, v1
	v_cvt_pk_bf16_f32 v165, v2, v3
	v_add_u32_e32 v157, 0x58100, v149
	global_store_dwordx4 v157, v[162:165], s[20:21]
	s_nop 1
	s_mov_b64 s[0:1], -1
	s_and_b64 vcc, exec, s[38:39]
	s_cbranch_vccnz .LBB0_284
	s_andn2_b64 vcc, exec, s[16:17]
	s_cbranch_vccnz .LBB0_283
	s_barrier
	s_branch .LBB0_283

; __device__ __forceinline__ u32x4 pack8(const float* v) { u32x4 w; w.x = pk2(v[0], v[1]); w.y = pk2(v[2], v[3]); w.z = pk2(v[4], v[5]); w.w = pk2(v[6], v[7]); return w; }
; __device__ __forceinline__ void unpack8(u32x4 w, float* v) { v[0] = bflo(w.x); v[1] = bfhi(w.x); v[2] = bflo(w.y); v[3] = bfhi(w.y); v[4] = bflo(w.z); v[5] = bfhi(w.z); v[6] = bflo(w.w); v[7] = bfhi(w.w); }
; #define EPI_LOOP_END asm volatile("" ::: "memory"); } }
;     __device__ __forceinline__ void operator()(const f32x4 (&acc)[2][2][4][2], const pg8::Unit& u, int wr, int wc, int fr, int fq) const {
;         EPI_LOOP_BEGIN
;             float g[8]; unpack8(*(const u32x4*)((const bf16_t*)(ws + O_GATES) + (size_t)t * 3072 + PASS * 1024 + c0), g);
;             bf16_t* mp = (bf16_t*)(ws + O_HM) + (size_t)t * 1024 + c0;
;             if (PASS > 0) { float pv[8]; unpack8(*(const u32x4*)mp, pv);
; #pragma unroll
;                 for (int e = 0; e < 8; ++e) v[e] = pv[e] + g[e] * v[e];
;             } else {
; #pragma unroll
;                 for (int e = 0; e < 8; ++e) v[e] *= g[e];
;             }
;             *(u32x4*)mp = pack8(v);
;         EPI_LOOP_END
;     }
.LBB0_318:
	s_lshl_b32 s0, s72, 8
	v_mov_b32_e32 v148, v37
	v_mov_b32_e32 v149, v41
	s_or_b32 s0, s0, s64
	v_mov_b64_e32 v[158:159], s[4:5]
	v_lshl_add_u32 v150, v148, 3, s0
	s_lshl_b32 s0, s73, 8
	s_add_i32 s0, s0, s63
	v_add_u32_e32 v156, s0, v149
	v_mul_u32_u24_e32 v148, 0x1800, v156
	v_lshl_add_u32 v148, v150, 1, v148
	v_lshlrev_b32_e32 v149, 11, v156
	v_lshl_add_u32 v149, v150, 1, v149
	s_add_u32 s18, s4, 0x12871000
	s_addc_u32 s19, s5, 0
	global_load_dwordx4 v[152:155], v148, s[18:19]
	global_load_dwordx4 v[190:193], v149, s[20:21]
	v_add_u32_e32 v151, 0x18000, v148
	global_load_dwordx4 v[178:181], v151, s[18:19]
	v_add_u32_e32 v157, 0x8000, v149
	global_load_dwordx4 v[194:197], v157, s[20:21]
	v_add_u32_e32 v151, 0x30000, v148
	global_load_dwordx4 v[182:185], v151, s[18:19]
	v_add_u32_e32 v157, 0x10000, v149
	global_load_dwordx4 v[204:207], v157, s[20:21]
	v_add_u32_e32 v151, 0x48000, v148
	global_load_dwordx4 v[186:189], v151, s[18:19]
	v_add_u32_e32 v157, 0x18000, v149
	global_load_dwordx4 v[208:211], v157, s[20:21]
	s_waitcnt vmcnt(6)
	v_lshlrev_b32_e32 v162, 16, v152
	v_and_b32_e32 v163, 0xffff0000, v152
	v_lshlrev_b32_e32 v164, 16, v153
	v_and_b32_e32 v165, 0xffff0000, v153
	v_lshlrev_b32_e32 v166, 16, v154
	v_and_b32_e32 v167, 0xffff0000, v154
	v_lshlrev_b32_e32 v168, 16, v155
	v_and_b32_e32 v169, 0xffff0000, v155
	v_lshlrev_b32_e32 v170, 16, v190
	v_and_b32_e32 v171, 0xffff0000, v190
	v_lshlrev_b32_e32 v172, 16, v191
	v_and_b32_e32 v173, 0xffff0000, v191
	v_lshlrev_b32_e32 v174, 16, v192
	v_and_b32_e32 v175, 0xffff0000, v192
	v_lshlrev_b32_e32 v176, 16, v193
	v_and_b32_e32 v177, 0xffff0000, v193
	v_pk_fma_f32 v[136:137], v[136:137], v[162:163], v[170:171]
	v_pk_fma_f32 v[138:139], v[138:139], v[164:165], v[172:173]
	v_pk_fma_f32 v[132:133], v[132:133], v[166:167], v[174:175]
	v_pk_fma_f32 v[134:135], v[134:135], v[168:169], v[176:177]
	v_cvt_pk_bf16_f32 v162, v136, v137
	v_cvt_pk_bf16_f32 v163, v138, v139
	v_cvt_pk_bf16_f32 v164, v132, v133
	v_cvt_pk_bf16_f32 v165, v134, v135
	global_store_dwordx4 v149, v[162:165], s[20:21]
	v_add_u32_e32 v151, 0xc0000, v148
	global_load_dwordx4 v[152:155], v151, s[18:19]
	v_add_u32_e32 v157, 0x40000, v149
	global_load_dwordx4 v[190:193], v157, s[20:21]
	s_waitcnt vmcnt(7)
	v_lshlrev_b32_e32 v162, 16, v178
	v_and_b32_e32 v163, 0xffff0000, v178
	v_lshlrev_b32_e32 v164, 16, v179
	v_and_b32_e32 v165, 0xffff0000, v179
	v_lshlrev_b32_e32 v166, 16, v180
	v_and_b32_e32 v167, 0xffff0000, v180
	v_lshlrev_b32_e32 v168, 16, v181
	v_and_b32_e32 v169, 0xffff0000, v181
	v_lshlrev_b32_e32 v170, 16, v194
	v_and_b32_e32 v171, 0xffff0000, v194
	v_lshlrev_b32_e32 v172, 16, v195
	v_and_b32_e32 v173, 0xffff0000, v195
	v_lshlrev_b32_e32 v174, 16, v196
	v_and_b32_e32 v175, 0xffff0000, v196
	v_lshlrev_b32_e32 v176, 16, v197
	v_and_b32_e32 v177, 0xffff0000, v197
	v_pk_fma_f32 v[128:129], v[128:129], v[162:163], v[170:171]
	v_pk_fma_f32 v[130:131], v[130:131], v[164:165], v[172:173]
	v_pk_fma_f32 v[124:125], v[124:125], v[166:167], v[174:175]
	v_pk_fma_f32 v[126:127], v[126:127], v[168:169], v[176:177]
	v_cvt_pk_bf16_f32 v162, v128, v129
	v_cvt_pk_bf16_f32 v163, v130, v131
	v_cvt_pk_bf16_f32 v164, v124, v125
	v_cvt_pk_bf16_f32 v165, v126, v127
	v_add_u32_e32 v157, 0x8000, v149
	global_store_dwordx4 v157, v[162:165], s[20:21]
	v_add_u32_e32 v151, 0xd8000, v148
	global_load_dwordx4 v[178:181], v151, s[18:19]
	v_add_u32_e32 v157, 0x48000, v149
	global_load_dwordx4 v[194:197], v157, s[20:21]
	s_waitcnt vmcnt(8)
	v_lshlrev_b32_e32 v162, 16, v182
	v_and_b32_e32 v163, 0xffff0000, v182
	v_lshlrev_b32_e32 v164, 16, v183
	v_and_b32_e32 v165, 0xffff0000, v183
	v_lshlrev_b32_e32 v166, 16, v184
	v_and_b32_e32 v167, 0xffff0000, v184
	v_lshlrev_b32_e32 v168, 16, v185
	v_and_b32_e32 v169, 0xffff0000, v185
	v_lshlrev_b32_e32 v170, 16, v204
	v_and_b32_e32 v171, 0xffff0000, v204
	v_lshlrev_b32_e32 v172, 16, v205
	v_and_b32_e32 v173, 0xffff0000, v205
	v_lshlrev_b32_e32 v174, 16, v206
	v_and_b32_e32 v175, 0xffff0000, v206
	v_lshlrev_b32_e32 v176, 16, v207
	v_and_b32_e32 v177, 0xffff0000, v207
	v_pk_fma_f32 v[120:121], v[120:121], v[162:163], v[170:171]
	v_pk_fma_f32 v[122:123], v[122:123], v[164:165], v[172:173]
	v_pk_fma_f32 v[116:117], v[116:117], v[166:167], v[174:175]
	v_pk_fma_f32 v[118:119], v[118:119], v[168:169], v[176:177]
	v_cvt_pk_bf16_f32 v162, v120, v121
	v_cvt_pk_bf16_f32 v163, v122, v123
	v_cvt_pk_bf16_f32 v164, v116, v117
	v_cvt_pk_bf16_f32 v165, v118, v119
	v_add_u32_e32 v157, 0x10000, v149
	global_store_dwordx4 v157, v[162:165], s[20:21]
	v_add_u32_e32 v151, 0xf0000, v148
	global_load_dwordx4 v[182:185], v151, s[18:19]
	v_add_u32_e32 v157, 0x50000, v149
	global_load_dwordx4 v[204:207], v157, s[20:21]
	s_waitcnt vmcnt(9)
	v_lshlrev_b32_e32 v162, 16, v186
	v_and_b32_e32 v163, 0xffff0000, v186
	v_lshlrev_b32_e32 v164, 16, v187
	v_and_b32_e32 v165, 0xffff0000, v187
	v_lshlrev_b32_e32 v166, 16, v188
	v_and_b32_e32 v167, 0xffff0000, v188
	v_lshlrev_b32_e32 v168, 16, v189
	v_and_b32_e32 v169, 0xffff0000, v189
	v_lshlrev_b32_e32 v170, 16, v208
	v_and_b32_e32 v171, 0xffff0000, v208
	v_lshlrev_b32_e32 v172, 16, v209
	v_and_b32_e32 v173, 0xffff0000, v209
	v_lshlrev_b32_e32 v174, 16, v210
	v_and_b32_e32 v175, 0xffff0000, v210
	v_lshlrev_b32_e32 v176, 16, v211
	v_and_b32_e32 v177, 0xffff0000, v211
	v_pk_fma_f32 v[112:113], v[112:113], v[162:163], v[170:171]
	v_pk_fma_f32 v[114:115], v[114:115], v[164:165], v[172:173]
	v_pk_fma_f32 v[108:109], v[108:109], v[166:167], v[174:175]
	v_pk_fma_f32 v[110:111], v[110:111], v[168:169], v[176:177]
	v_cvt_pk_bf16_f32 v162, v112, v113
	v_cvt_pk_bf16_f32 v163, v114, v115
	v_cvt_pk_bf16_f32 v164, v108, v109
	v_cvt_pk_bf16_f32 v165, v110, v111
	v_add_u32_e32 v157, 0x18000, v149
	global_store_dwordx4 v157, v[162:165], s[20:21]
	v_add_u32_e32 v151, 0x108000, v148
	global_load_dwordx4 v[186:189], v151, s[18:19]
	v_add_u32_e32 v157, 0x58000, v149
	global_load_dwordx4 v[208:211], v157, s[20:21]
	s_waitcnt vmcnt(9)
; __device__ __forceinline__ u32x4 pack8(const float* v) { u32x4 w; w.x = pk2(v[0], v[1]); w.y = pk2(v[2], v[3]); w.z = pk2(v[4], v[5]); w.w = pk2(v[6], v[7]); return w; }
; __device__ __forceinline__ void unpack8(u32x4 w, float* v) { v[0] = bflo(w.x); v[1] = bfhi(w.x); v[2] = bflo(w.y); v[3] = bfhi(w.y); v[4] = bflo(w.z); v[5] = bfhi(w.z); v[6] = bflo(w.w); v[7] = bfhi(w.w); }
; #define EPI_LOOP_END asm volatile("" ::: "memory"); } }
;     __device__ __forceinline__ void operator()(const f32x4 (&acc)[2][2][4][2], const pg8::Unit& u, int wr, int wc, int fr, int fq) const {
;         EPI_LOOP_BEGIN
;             float g[8]; unpack8(*(const u32x4*)((const bf16_t*)(ws + O_GATES) + (size_t)t * 3072 + PASS * 1024 + c0), g);
;             bf16_t* mp = (bf16_t*)(ws + O_HM) + (size_t)t * 1024 + c0;
;             if (PASS > 0) { float pv[8]; unpack8(*(const u32x4*)mp, pv);
; #pragma unroll
;                 for (int e = 0; e < 8; ++e) v[e] = pv[e] + g[e] * v[e];
;             } else {
; #pragma unroll
;                 for (int e = 0; e < 8; ++e) v[e] *= g[e];
;             }
;             *(u32x4*)mp = pack8(v);
;         EPI_LOOP_END
;     }
	v_lshlrev_b32_e32 v162, 16, v152
	v_and_b32_e32 v163, 0xffff0000, v152
	v_lshlrev_b32_e32 v164, 16, v153
	v_and_b32_e32 v165, 0xffff0000, v153
	v_lshlrev_b32_e32 v166, 16, v154
	v_and_b32_e32 v167, 0xffff0000, v154
	v_lshlrev_b32_e32 v168, 16, v155
	v_and_b32_e32 v169, 0xffff0000, v155
	v_lshlrev_b32_e32 v170, 16, v190
	v_and_b32_e32 v171, 0xffff0000, v190
	v_lshlrev_b32_e32 v172, 16, v191
	v_and_b32_e32 v173, 0xffff0000, v191
	v_lshlrev_b32_e32 v174, 16, v192
	v_and_b32_e32 v175, 0xffff0000, v192
	v_lshlrev_b32_e32 v176, 16, v193
	v_and_b32_e32 v177, 0xffff0000, v193
	v_pk_fma_f32 v[104:105], v[104:105], v[162:163], v[170:171]
	v_pk_fma_f32 v[106:107], v[106:107], v[164:165], v[172:173]
	v_pk_fma_f32 v[100:101], v[100:101], v[166:167], v[174:175]
	v_pk_fma_f32 v[102:103], v[102:103], v[168:169], v[176:177]
	v_cvt_pk_bf16_f32 v162, v104, v105
	v_cvt_pk_bf16_f32 v163, v106, v107
	v_cvt_pk_bf16_f32 v164, v100, v101
	v_cvt_pk_bf16_f32 v165, v102, v103
	v_add_u32_e32 v157, 0x40000, v149
	global_store_dwordx4 v157, v[162:165], s[20:21]
	v_add_u32_e32 v151, 0x100, v148
	global_load_dwordx4 v[152:155], v151, s[18:19]
	v_add_u32_e32 v157, 0x100, v149
	global_load_dwordx4 v[190:193], v157, s[20:21]
	s_waitcnt vmcnt(9)
	v_lshlrev_b32_e32 v162, 16, v178
	v_and_b32_e32 v163, 0xffff0000, v178
	v_lshlrev_b32_e32 v164, 16, v179
	v_and_b32_e32 v165, 0xffff0000, v179
	v_lshlrev_b32_e32 v166, 16, v180
	v_and_b32_e32 v167, 0xffff0000, v180
	v_lshlrev_b32_e32 v168, 16, v181
	v_and_b32_e32 v169, 0xffff0000, v181
	v_lshlrev_b32_e32 v170, 16, v194
	v_and_b32_e32 v171, 0xffff0000, v194
	v_lshlrev_b32_e32 v172, 16, v195
	v_and_b32_e32 v173, 0xffff0000, v195
	v_lshlrev_b32_e32 v174, 16, v196
	v_and_b32_e32 v175, 0xffff0000, v196
	v_lshlrev_b32_e32 v176, 16, v197
	v_and_b32_e32 v177, 0xffff0000, v197
	v_pk_fma_f32 v[96:97], v[96:97], v[162:163], v[170:171]
	v_pk_fma_f32 v[98:99], v[98:99], v[164:165], v[172:173]
	v_pk_fma_f32 v[92:93], v[92:93], v[166:167], v[174:175]
	v_pk_fma_f32 v[94:95], v[94:95], v[168:169], v[176:177]
	v_cvt_pk_bf16_f32 v162, v96, v97
	v_cvt_pk_bf16_f32 v163, v98, v99
	v_cvt_pk_bf16_f32 v164, v92, v93
	v_cvt_pk_bf16_f32 v165, v94, v95
	v_add_u32_e32 v157, 0x48000, v149
	global_store_dwordx4 v157, v[162:165], s[20:21]
	v_add_u32_e32 v151, 0x18100, v148
	global_load_dwordx4 v[178:181], v151, s[18:19]
	v_add_u32_e32 v157, 0x8100, v149
	global_load_dwordx4 v[194:197], v157, s[20:21]
	s_waitcnt vmcnt(9)
	v_lshlrev_b32_e32 v162, 16, v182
	v_and_b32_e32 v163, 0xffff0000, v182
	v_lshlrev_b32_e32 v164, 16, v183
	v_and_b32_e32 v165, 0xffff0000, v183
	v_lshlrev_b32_e32 v166, 16, v184
	v_and_b32_e32 v167, 0xffff0000, v184
	v_lshlrev_b32_e32 v168, 16, v185
	v_and_b32_e32 v169, 0xffff0000, v185
	v_lshlrev_b32_e32 v170, 16, v204
	v_and_b32_e32 v171, 0xffff0000, v204
	v_lshlrev_b32_e32 v172, 16, v205
	v_and_b32_e32 v173, 0xffff0000, v205
	v_lshlrev_b32_e32 v174, 16, v206
	v_and_b32_e32 v175, 0xffff0000, v206
	v_lshlrev_b32_e32 v176, 16, v207
	v_and_b32_e32 v177, 0xffff0000, v207
	v_pk_fma_f32 v[88:89], v[88:89], v[162:163], v[170:171]
	v_pk_fma_f32 v[90:91], v[90:91], v[164:165], v[172:173]
	v_pk_fma_f32 v[84:85], v[84:85], v[166:167], v[174:175]
	v_pk_fma_f32 v[86:87], v[86:87], v[168:169], v[176:177]
	v_cvt_pk_bf16_f32 v162, v88, v89
	v_cvt_pk_bf16_f32 v163, v90, v91
	v_cvt_pk_bf16_f32 v164, v84, v85
	v_cvt_pk_bf16_f32 v165, v86, v87
	v_add_u32_e32 v157, 0x50000, v149
	global_store_dwordx4 v157, v[162:165], s[20:21]
	v_add_u32_e32 v151, 0x30100, v148
	global_load_dwordx4 v[182:185], v151, s[18:19]
	v_add_u32_e32 v157, 0x10100, v149
	global_load_dwordx4 v[204:207], v157, s[20:21]
	s_waitcnt vmcnt(9)
	v_lshlrev_b32_e32 v162, 16, v186
	v_and_b32_e32 v163, 0xffff0000, v186
	v_lshlrev_b32_e32 v164, 16, v187
	v_and_b32_e32 v165, 0xffff0000, v187
	v_lshlrev_b32_e32 v166, 16, v188
	v_and_b32_e32 v167, 0xffff0000, v188
	v_lshlrev_b32_e32 v168, 16, v189
	v_and_b32_e32 v169, 0xffff0000, v189
	v_lshlrev_b32_e32 v170, 16, v208
	v_and_b32_e32 v171, 0xffff0000, v208
	v_lshlrev_b32_e32 v172, 16, v209
	v_and_b32_e32 v173, 0xffff0000, v209
	v_lshlrev_b32_e32 v174, 16, v210
	v_and_b32_e32 v175, 0xffff0000, v210
	v_lshlrev_b32_e32 v176, 16, v211
	v_and_b32_e32 v177, 0xffff0000, v211
	v_pk_fma_f32 v[80:81], v[80:81], v[162:163], v[170:171]
	v_pk_fma_f32 v[82:83], v[82:83], v[164:165], v[172:173]
	v_pk_fma_f32 v[76:77], v[76:77], v[166:167], v[174:175]
	v_pk_fma_f32 v[78:79], v[78:79], v[168:169], v[176:177]
	v_cvt_pk_bf16_f32 v162, v80, v81
	v_cvt_pk_bf16_f32 v163, v82, v83
	v_cvt_pk_bf16_f32 v164, v76, v77
	v_cvt_pk_bf16_f32 v165, v78, v79
	v_add_u32_e32 v157, 0x58000, v149
	global_store_dwordx4 v157, v[162:165], s[20:21]
	v_add_u32_e32 v151, 0x48100, v148
	global_load_dwordx4 v[186:189], v151, s[18:19]
	v_add_u32_e32 v157, 0x18100, v149
	global_load_dwordx4 v[208:211], v157, s[20:21]
	s_waitcnt vmcnt(9)
	v_lshlrev_b32_e32 v162, 16, v152
	v_and_b32_e32 v163, 0xffff0000, v152
	v_lshlrev_b32_e32 v164, 16, v153
	v_and_b32_e32 v165, 0xffff0000, v153
	v_lshlrev_b32_e32 v166, 16, v154
	v_and_b32_e32 v167, 0xffff0000, v154
	v_lshlrev_b32_e32 v168, 16, v155
	v_and_b32_e32 v169, 0xffff0000, v155
	v_lshlrev_b32_e32 v170, 16, v190
	v_and_b32_e32 v171, 0xffff0000, v190
	v_lshlrev_b32_e32 v172, 16, v191
	v_and_b32_e32 v173, 0xffff0000, v191
	v_lshlrev_b32_e32 v174, 16, v192
	v_and_b32_e32 v175, 0xffff0000, v192
	v_lshlrev_b32_e32 v176, 16, v193
	v_and_b32_e32 v177, 0xffff0000, v193
	v_pk_fma_f32 v[72:73], v[72:73], v[162:163], v[170:171]
	v_pk_fma_f32 v[74:75], v[74:75], v[164:165], v[172:173]
	v_pk_fma_f32 v[68:69], v[68:69], v[166:167], v[174:175]
	v_pk_fma_f32 v[70:71], v[70:71], v[168:169], v[176:177]
	v_cvt_pk_bf16_f32 v162, v72, v73
	v_cvt_pk_bf16_f32 v163, v74, v75
	v_cvt_pk_bf16_f32 v164, v68, v69
	v_cvt_pk_bf16_f32 v165, v70, v71
	v_add_u32_e32 v157, 0x100, v149
	global_store_dwordx4 v157, v[162:165], s[20:21]
	v_add_u32_e32 v151, 0xc0100, v148
	global_load_dwordx4 v[152:155], v151, s[18:19]
	v_add_u32_e32 v157, 0x40100, v149
	global_load_dwordx4 v[190:193], v157, s[20:21]
	s_waitcnt vmcnt(9)
; __device__ __forceinline__ u32x4 pack8(const float* v) { u32x4 w; w.x = pk2(v[0], v[1]); w.y = pk2(v[2], v[3]); w.z = pk2(v[4], v[5]); w.w = pk2(v[6], v[7]); return w; }
; __device__ __forceinline__ void unpack8(u32x4 w, float* v) { v[0] = bflo(w.x); v[1] = bfhi(w.x); v[2] = bflo(w.y); v[3] = bfhi(w.y); v[4] = bflo(w.z); v[5] = bfhi(w.z); v[6] = bflo(w.w); v[7] = bfhi(w.w); }
; #define EPI_LOOP_END asm volatile("" ::: "memory"); } }
;     __device__ __forceinline__ void operator()(const f32x4 (&acc)[2][2][4][2], const pg8::Unit& u, int wr, int wc, int fr, int fq) const {
;         EPI_LOOP_BEGIN
;             float g[8]; unpack8(*(const u32x4*)((const bf16_t*)(ws + O_GATES) + (size_t)t * 3072 + PASS * 1024 + c0), g);
;             bf16_t* mp = (bf16_t*)(ws + O_HM) + (size_t)t * 1024 + c0;
;             if (PASS > 0) { float pv[8]; unpack8(*(const u32x4*)mp, pv);
; #pragma unroll
;                 for (int e = 0; e < 8; ++e) v[e] = pv[e] + g[e] * v[e];
;             } else {
; #pragma unroll
;                 for (int e = 0; e < 8; ++e) v[e] *= g[e];
;             }
;             *(u32x4*)mp = pack8(v);
;         EPI_LOOP_END
;     }
	v_lshlrev_b32_e32 v162, 16, v178
	v_and_b32_e32 v163, 0xffff0000, v178
	v_lshlrev_b32_e32 v164, 16, v179
	v_and_b32_e32 v165, 0xffff0000, v179
	v_lshlrev_b32_e32 v166, 16, v180
	v_and_b32_e32 v167, 0xffff0000, v180
	v_lshlrev_b32_e32 v168, 16, v181
	v_and_b32_e32 v169, 0xffff0000, v181
	v_lshlrev_b32_e32 v170, 16, v194
	v_and_b32_e32 v171, 0xffff0000, v194
	v_lshlrev_b32_e32 v172, 16, v195
	v_and_b32_e32 v173, 0xffff0000, v195
	v_lshlrev_b32_e32 v174, 16, v196
	v_and_b32_e32 v175, 0xffff0000, v196
	v_lshlrev_b32_e32 v176, 16, v197
	v_and_b32_e32 v177, 0xffff0000, v197
	v_pk_fma_f32 v[64:65], v[64:65], v[162:163], v[170:171]
	v_pk_fma_f32 v[66:67], v[66:67], v[164:165], v[172:173]
	v_pk_fma_f32 v[60:61], v[60:61], v[166:167], v[174:175]
	v_pk_fma_f32 v[62:63], v[62:63], v[168:169], v[176:177]
	v_cvt_pk_bf16_f32 v162, v64, v65
	v_cvt_pk_bf16_f32 v163, v66, v67
	v_cvt_pk_bf16_f32 v164, v60, v61
	v_cvt_pk_bf16_f32 v165, v62, v63
	v_add_u32_e32 v157, 0x8100, v149
	global_store_dwordx4 v157, v[162:165], s[20:21]
	v_add_u32_e32 v151, 0xd8100, v148
	global_load_dwordx4 v[178:181], v151, s[18:19]
	v_add_u32_e32 v157, 0x48100, v149
	global_load_dwordx4 v[194:197], v157, s[20:21]
	s_waitcnt vmcnt(9)
	v_lshlrev_b32_e32 v162, 16, v182
	v_and_b32_e32 v163, 0xffff0000, v182
	v_lshlrev_b32_e32 v164, 16, v183
	v_and_b32_e32 v165, 0xffff0000, v183
	v_lshlrev_b32_e32 v166, 16, v184
	v_and_b32_e32 v167, 0xffff0000, v184
	v_lshlrev_b32_e32 v168, 16, v185
	v_and_b32_e32 v169, 0xffff0000, v185
	v_lshlrev_b32_e32 v170, 16, v204
	v_and_b32_e32 v171, 0xffff0000, v204
	v_lshlrev_b32_e32 v172, 16, v205
	v_and_b32_e32 v173, 0xffff0000, v205
	v_lshlrev_b32_e32 v174, 16, v206
	v_and_b32_e32 v175, 0xffff0000, v206
	v_lshlrev_b32_e32 v176, 16, v207
	v_and_b32_e32 v177, 0xffff0000, v207
	v_pk_fma_f32 v[56:57], v[56:57], v[162:163], v[170:171]
	v_pk_fma_f32 v[58:59], v[58:59], v[164:165], v[172:173]
	v_pk_fma_f32 v[52:53], v[52:53], v[166:167], v[174:175]
	v_pk_fma_f32 v[54:55], v[54:55], v[168:169], v[176:177]
	v_cvt_pk_bf16_f32 v162, v56, v57
	v_cvt_pk_bf16_f32 v163, v58, v59
	v_cvt_pk_bf16_f32 v164, v52, v53
	v_cvt_pk_bf16_f32 v165, v54, v55
	v_add_u32_e32 v157, 0x10100, v149
	global_store_dwordx4 v157, v[162:165], s[20:21]
	v_add_u32_e32 v151, 0xf0100, v148
	global_load_dwordx4 v[182:185], v151, s[18:19]
	v_add_u32_e32 v157, 0x50100, v149
	global_load_dwordx4 v[204:207], v157, s[20:21]
	s_waitcnt vmcnt(9)
	v_lshlrev_b32_e32 v162, 16, v186
	v_and_b32_e32 v163, 0xffff0000, v186
	v_lshlrev_b32_e32 v164, 16, v187
	v_and_b32_e32 v165, 0xffff0000, v187
	v_lshlrev_b32_e32 v166, 16, v188
	v_and_b32_e32 v167, 0xffff0000, v188
	v_lshlrev_b32_e32 v168, 16, v189
	v_and_b32_e32 v169, 0xffff0000, v189
	v_lshlrev_b32_e32 v170, 16, v208
	v_and_b32_e32 v171, 0xffff0000, v208
	v_lshlrev_b32_e32 v172, 16, v209
	v_and_b32_e32 v173, 0xffff0000, v209
	v_lshlrev_b32_e32 v174, 16, v210
	v_and_b32_e32 v175, 0xffff0000, v210
	v_lshlrev_b32_e32 v176, 16, v211
	v_and_b32_e32 v177, 0xffff0000, v211
	v_pk_fma_f32 v[48:49], v[48:49], v[162:163], v[170:171]
	v_pk_fma_f32 v[50:51], v[50:51], v[164:165], v[172:173]
	v_pk_fma_f32 v[32:33], v[32:33], v[166:167], v[174:175]
	v_pk_fma_f32 v[34:35], v[34:35], v[168:169], v[176:177]
	v_cvt_pk_bf16_f32 v162, v48, v49
	v_cvt_pk_bf16_f32 v163, v50, v51
	v_cvt_pk_bf16_f32 v164, v32, v33
	v_cvt_pk_bf16_f32 v165, v34, v35
	v_add_u32_e32 v157, 0x18100, v149
	global_store_dwordx4 v157, v[162:165], s[20:21]
	v_add_u32_e32 v151, 0x108100, v148
	global_load_dwordx4 v[186:189], v151, s[18:19]
	v_add_u32_e32 v157, 0x58100, v149
	global_load_dwordx4 v[208:211], v157, s[20:21]
	s_waitcnt vmcnt(9)
; __device__ __forceinline__ u32x4 pack8(const float* v) { u32x4 w; w.x = pk2(v[0], v[1]); w.y = pk2(v[2], v[3]); w.z = pk2(v[4], v[5]); w.w = pk2(v[6], v[7]); return w; }
; __device__ __forceinline__ void unpack8(u32x4 w, float* v) { v[0] = bflo(w.x); v[1] = bfhi(w.x); v[2] = bflo(w.y); v[3] = bfhi(w.y); v[4] = bflo(w.z); v[5] = bfhi(w.z); v[6] = bflo(w.w); v[7] = bfhi(w.w); }
; #define EPI_LOOP_END asm volatile("" ::: "memory"); } }
;     __device__ __forceinline__ void operator()(const f32x4 (&acc)[2][2][4][2], const pg8::Unit& u, int wr, int wc, int fr, int fq) const {
;         EPI_LOOP_BEGIN
;             float g[8]; unpack8(*(const u32x4*)((const bf16_t*)(ws + O_GATES) + (size_t)t * 3072 + PASS * 1024 + c0), g);
;             bf16_t* mp = (bf16_t*)(ws + O_HM) + (size_t)t * 1024 + c0;
;             if (PASS > 0) { float pv[8]; unpack8(*(const u32x4*)mp, pv);
; #pragma unroll
;                 for (int e = 0; e < 8; ++e) v[e] = pv[e] + g[e] * v[e];
;             } else {
; #pragma unroll
;                 for (int e = 0; e < 8; ++e) v[e] *= g[e];
;             }
;             *(u32x4*)mp = pack8(v);
;         EPI_LOOP_END
;     }
	v_lshlrev_b32_e32 v162, 16, v152
	v_and_b32_e32 v163, 0xffff0000, v152
	v_lshlrev_b32_e32 v164, 16, v153
	v_and_b32_e32 v165, 0xffff0000, v153
	v_lshlrev_b32_e32 v166, 16, v154
	v_and_b32_e32 v167, 0xffff0000, v154
	v_lshlrev_b32_e32 v168, 16, v155
	v_and_b32_e32 v169, 0xffff0000, v155
	v_lshlrev_b32_e32 v170, 16, v190
	v_and_b32_e32 v171, 0xffff0000, v190
	v_lshlrev_b32_e32 v172, 16, v191
	v_and_b32_e32 v173, 0xffff0000, v191
	v_lshlrev_b32_e32 v174, 16, v192
	v_and_b32_e32 v175, 0xffff0000, v192
	v_lshlrev_b32_e32 v176, 16, v193
	v_and_b32_e32 v177, 0xffff0000, v193
	v_pk_fma_f32 v[28:29], v[28:29], v[162:163], v[170:171]
	v_pk_fma_f32 v[30:31], v[30:31], v[164:165], v[172:173]
	v_pk_fma_f32 v[24:25], v[24:25], v[166:167], v[174:175]
	v_pk_fma_f32 v[26:27], v[26:27], v[168:169], v[176:177]
	v_cvt_pk_bf16_f32 v162, v28, v29
	v_cvt_pk_bf16_f32 v163, v30, v31
	v_cvt_pk_bf16_f32 v164, v24, v25
	v_cvt_pk_bf16_f32 v165, v26, v27
	v_add_u32_e32 v157, 0x40100, v149
	global_store_dwordx4 v157, v[162:165], s[20:21]
	s_nop 1
	s_waitcnt vmcnt(7)
	v_lshlrev_b32_e32 v162, 16, v178
	v_and_b32_e32 v163, 0xffff0000, v178
	v_lshlrev_b32_e32 v164, 16, v179
	v_and_b32_e32 v165, 0xffff0000, v179
	v_lshlrev_b32_e32 v166, 16, v180
	v_and_b32_e32 v167, 0xffff0000, v180
	v_lshlrev_b32_e32 v168, 16, v181
	v_and_b32_e32 v169, 0xffff0000, v181
	v_lshlrev_b32_e32 v170, 16, v194
	v_and_b32_e32 v171, 0xffff0000, v194
	v_lshlrev_b32_e32 v172, 16, v195
	v_and_b32_e32 v173, 0xffff0000, v195
	v_lshlrev_b32_e32 v174, 16, v196
	v_and_b32_e32 v175, 0xffff0000, v196
	v_lshlrev_b32_e32 v176, 16, v197
	v_and_b32_e32 v177, 0xffff0000, v197
	v_pk_fma_f32 v[20:21], v[20:21], v[162:163], v[170:171]
	v_pk_fma_f32 v[22:23], v[22:23], v[164:165], v[172:173]
	v_pk_fma_f32 v[16:17], v[16:17], v[166:167], v[174:175]
	v_pk_fma_f32 v[18:19], v[18:19], v[168:169], v[176:177]
	v_cvt_pk_bf16_f32 v162, v20, v21
	v_cvt_pk_bf16_f32 v163, v22, v23
	v_cvt_pk_bf16_f32 v164, v16, v17
	v_cvt_pk_bf16_f32 v165, v18, v19
	v_add_u32_e32 v157, 0x48100, v149
	global_store_dwordx4 v157, v[162:165], s[20:21]
	s_nop 1
	s_waitcnt vmcnt(5)
	v_lshlrev_b32_e32 v162, 16, v182
	v_and_b32_e32 v163, 0xffff0000, v182
	v_lshlrev_b32_e32 v164, 16, v183
	v_and_b32_e32 v165, 0xffff0000, v183
	v_lshlrev_b32_e32 v166, 16, v184
	v_and_b32_e32 v167, 0xffff0000, v184
	v_lshlrev_b32_e32 v168, 16, v185
	v_and_b32_e32 v169, 0xffff0000, v185
	v_lshlrev_b32_e32 v170, 16, v204
	v_and_b32_e32 v171, 0xffff0000, v204
	v_lshlrev_b32_e32 v172, 16, v205
	v_and_b32_e32 v173, 0xffff0000, v205
	v_lshlrev_b32_e32 v174, 16, v206
	v_and_b32_e32 v175, 0xffff0000, v206
	v_lshlrev_b32_e32 v176, 16, v207
	v_and_b32_e32 v177, 0xffff0000, v207
	v_pk_fma_f32 v[12:13], v[12:13], v[162:163], v[170:171]
	v_pk_fma_f32 v[14:15], v[14:15], v[164:165], v[172:173]
	v_pk_fma_f32 v[8:9], v[8:9], v[166:167], v[174:175]
	v_pk_fma_f32 v[10:11], v[10:11], v[168:169], v[176:177]
	v_cvt_pk_bf16_f32 v162, v12, v13
	v_cvt_pk_bf16_f32 v163, v14, v15
	v_cvt_pk_bf16_f32 v164, v8, v9
	v_cvt_pk_bf16_f32 v165, v10, v11
	v_add_u32_e32 v157, 0x50100, v149
	global_store_dwordx4 v157, v[162:165], s[20:21]
	s_nop 1
	s_waitcnt vmcnt(3)
	v_lshlrev_b32_e32 v162, 16, v186
	v_and_b32_e32 v163, 0xffff0000, v186
	v_lshlrev_b32_e32 v164, 16, v187
	v_and_b32_e32 v165, 0xffff0000, v187
	v_lshlrev_b32_e32 v166, 16, v188
	v_and_b32_e32 v167, 0xffff0000, v188
	v_lshlrev_b32_e32 v168, 16, v189
	v_and_b32_e32 v169, 0xffff0000, v189
	v_lshlrev_b32_e32 v170, 16, v208
	v_and_b32_e32 v171, 0xffff0000, v208
	v_lshlrev_b32_e32 v172, 16, v209
	v_and_b32_e32 v173, 0xffff0000, v209
	v_lshlrev_b32_e32 v174, 16, v210
	v_and_b32_e32 v175, 0xffff0000, v210
	v_lshlrev_b32_e32 v176, 16, v211
	v_and_b32_e32 v177, 0xffff0000, v211
	v_pk_fma_f32 v[4:5], v[4:5], v[162:163], v[170:171]
	v_pk_fma_f32 v[6:7], v[6:7], v[164:165], v[172:173]
	v_pk_fma_f32 v[0:1], v[0:1], v[166:167], v[174:175]
	v_pk_fma_f32 v[2:3], v[2:3], v[168:169], v[176:177]
	v_cvt_pk_bf16_f32 v162, v4, v5
	v_cvt_pk_bf16_f32 v163, v6, v7
	v_cvt_pk_bf16_f32 v164, v0, v1
	v_cvt_pk_bf16_f32 v165, v2, v3
	v_add_u32_e32 v157, 0x58100, v149
	global_store_dwordx4 v157, v[162:165], s[20:21]
	s_nop 1
	s_mov_b64 s[0:1], -1
	s_and_b64 vcc, exec, s[38:39]
	s_cbranch_vccnz .LBB0_305
	s_andn2_b64 vcc, exec, s[16:17]
	s_cbranch_vccnz .LBB0_304
	s_barrier
	s_branch .LBB0_304
